# prep phase: hgrn_prep second-half q/f loads prefetched in first half; gdn_prep job top reordered (row loads before conv-weight load, beta/g pointers loaded once); attn_prep 5/1 job split
# speedup vs baseline: 1.0061x; 1.0061x over previous
; #define GAS __attribute__((address_space(1)))
; #define LAS __attribute__((address_space(3)))
; #define LDS_WAIT() asm volatile("s_waitcnt lgkmcnt(0)" ::: "memory")
; DI float fexp(float x) { return __builtin_amdgcn_exp2f(x * 1.4426950408889634f); }
; DI float sigm(float x) { return frcp(1.f + fexp(-x)); }
; DI float softplus(float x) { return fmaxf(x, 0.f) + flog(1.f + fexp(-fabsf(x))); }
;     const int bh = job >> 6, ch = job & 63, b = bh / 6, h = bh % 6, tid = F.tid, lane = F.lane, wave = F.wave;
;     const int t0 = ch * 64; const size_t m0 = (size_t)b * SEQ + t0;
;     LAS unsigned char* L = F.lds;
;     const bf16* P = (const bf16*)(F.ws + WS_P);
;     const float* PBA = (const float*)(F.ws + WS_PBA);
;     LAS float* BETA = (LAS float*)(L + gp::SM); LAS float* BC = BETA + 64;
;     const size_t cidx = (size_t)bh * 64 + ch;
;     if (tid < 384) { const int j = tid / 96, i96 = tid % 96, seg = i96 >> 5, c4 = (i96 & 31) * 4;
;         const f32x4 cwv = *(const GAS f32x4*)(F.in[15] + ((size_t)layer * 4 + j) * 2304 + seg * 768 + h * 128 + c4);
;         *(LAS f32x4*)(L + gp::CW + (j * 384 + seg * 128 + c4) * 4) = cwv; }
;     if (wave == 0) {
;         const float* pba = PBA + (m0 + lane) * 16;
;         const float beta = sigm(pba[h]);
;         float g = -fexp(F.in[16][layer * 6 + h]) * softplus(pba[6 + h] + F.in[17][layer * 6 + h]);
; #pragma unroll
;         for (int o = 1; o < 64; o <<= 1) { const float v = __shfl_up(g, o); if (lane >= o) g += v; }
;         const float blast = __shfl(g, 63);
;         BETA[lane] = beta; BC[lane] = g;
;         if (lane == 0) { BC[64] = blast; ((float*)(F.ws + WS_GE))[cidx] = fexp(blast); }
;     }
;     LDS_WAIT(); __syncthreads();
;     const float blast = BC[64];
;         const int t2 = tid >> 3, c02 = 16 * (tid & 7);
;         const int pcol2 = PC_V + h * 128 + c02, wch2 = 1536 + h * 128 + c02;
;         float av[16];
.LBB0_711:
	v_readlane_b32 s30, v252, 3
	s_cmp_le_i32 s30, s2
	s_cselect_b64 s[54:55], -1, 0
	s_and_b64 s[0:1], s[54:55], s[0:1]
	s_andn2_b64 vcc, exec, s[0:1]
	v_readlane_b32 s31, v252, 4
	s_cbranch_vccnz .LBB0_827
	s_waitcnt vmcnt(0)
	v_mbcnt_lo_u32_b32 v0, -1, 0
	v_mbcnt_hi_u32_b32 v0, -1, v0
	s_mov_b64 s[60:61], s[86:87]
	s_waitcnt lgkmcnt(0)
	v_add_u32_e32 v1, s81, v0
	s_mov_b64 s[0:1], s[84:85]
	v_writelane_b32 v255, s54, 19
	v_readlane_b32 s0, v253, 31
	v_readlane_b32 s1, v253, 32
	v_writelane_b32 v255, s55, 20
	s_mov_b32 s30, 0x2aaaaaab
	v_readfirstlane_b32 s39, v1
	s_and_b64 vcc, exec, s[0:1]
	s_cbranch_vccz .LBB0_807
	v_mul_hi_i32 v0, v1, s30
	v_lshrrev_b32_e32 v2, 31, v0
	v_ashrrev_i32_e32 v0, 4, v0
	v_readlane_b32 s0, v255, 17
	v_add_u32_e32 v2, v0, v2
	s_lshl_b32 s2, s0, 2
	v_ashrrev_i32_e32 v3, 31, v2
	s_movk_i32 s30, 0x60
	v_lshl_add_u64 v[4:5], v[2:3], 0, s[2:3]
	s_movk_i32 s2, 0x2400
	v_and_b32_e32 v71, 63, v1
	v_mul_lo_u32 v0, v2, s30
	v_mad_u64_u32 v[64:65], s[30:31], v4, s2, 0
	s_ashr_i32 s36, s39, 6
	v_cmp_gt_u32_e64 s[30:31], 2, v71
	s_add_u32 s0, s60, 0x32500000
	s_addc_u32 s1, s61, 0
	v_writelane_b32 v255, s30, 21
	s_add_u32 s78, s60, 0x39d00000
	s_addc_u32 s79, s61, 0
	v_writelane_b32 v255, s31, 22
	v_cmp_gt_u32_e64 s[30:31], 4, v71
	s_movk_i32 s34, 0x180
	v_sub_u32_e32 v0, v1, v0
	v_writelane_b32 v255, s30, 23
	s_cmp_lt_u32 s39, 64
	v_ashrrev_i32_e32 v6, 5, v0
	v_writelane_b32 v255, s31, 24
	v_cmp_gt_u32_e64 s[30:31], 8, v71
	v_lshlrev_b32_e32 v0, 2, v0
	v_mad_i32_i24 v65, v5, s2, v65
	v_writelane_b32 v255, s30, 25
	s_movk_i32 s2, 0x300
	v_mul_lo_u32 v2, v2, s34
	s_cselect_b64 s[80:81], -1, 0
	s_cmp_gt_u32 s39, 63
	v_writelane_b32 v255, s31, 26
	v_cmp_gt_u32_e64 s[30:31], 16, v71
	v_cmp_gt_i32_e64 s[40:41], s34, v1
	v_and_b32_e32 v0, 0x7c, v0
	v_mul_lo_u32 v66, v6, s2
	v_lshl_add_u32 v2, v6, 7, v2
	s_cselect_b64 s[34:35], -1, 0
	v_writelane_b32 v255, s30, 27
	s_add_i32 s2, 0, 0x1ed00
	v_or_b32_e32 v2, v2, v0
	v_writelane_b32 v255, s31, 28
	s_add_u32 s30, s60, 0x44050000
	v_lshlrev_b32_e32 v3, 2, v2
	v_lshlrev_b32_e32 v2, 2, v71
	v_readlane_b32 s46, v254, 55
	v_writelane_b32 v255, s30, 29
	s_addc_u32 s30, s61, 0
	v_and_b32_e32 v8, 7, v1
	v_add_u32_e32 v73, s46, v2
	v_add_u32_e32 v101, s2, v2
	v_writelane_b32 v255, s30, 30
	v_lshlrev_b32_e32 v2, 6, v8
	v_readlane_b32 s30, v254, 56
	v_and_b32_e32 v4, 4, v1
	v_cmp_ne_u32_e64 s[54:55], 0, v4
	v_add_u32_e32 v133, s30, v2
	v_readlane_b32 s30, v254, 57
	v_mov_b32_e32 v4, 0x1500
	v_mov_b32_e32 v5, 0x1200
	v_add_u32_e32 v134, s30, v2
	v_readlane_b32 s30, v254, 58
	v_ashrrev_i32_e32 v130, 3, v1
	v_and_b32_e32 v6, 3, v1
	v_add_u32_e32 v135, s30, v2
	v_readlane_b32 s30, v254, 59
	v_mul_lo_u32 v10, v130, s7
	v_lshlrev_b32_e32 v12, 1, v130
	v_add_u32_e32 v136, s30, v2
	v_bfe_u32 v2, v1, 2, 1
	v_cmp_eq_u32_e32 vcc, 0, v2
	v_lshlrev_b32_e32 v2, 9, v2
	v_readlane_b32 s30, v254, 60
	v_cndmask_b32_e32 v4, v4, v5, vcc
	v_lshl_or_b32 v137, v6, 5, v4
	v_lshlrev_b32_e32 v4, 7, v6
	v_add3_u32 v138, s30, v2, v4
	v_lshlrev_b32_e32 v4, 2, v130
	v_add_u32_e32 v2, 0, v10
	s_movk_i32 s30, 0xfef2
	v_add_u32_e32 v139, s2, v4
	v_add_u32_e32 v140, s46, v4
	v_mad_u64_u32 v[4:5], s[30:31], v130, s30, v[2:3]
	v_readlane_b32 s30, v254, 61
	v_lshrrev_b32_e32 v7, 5, v1
	v_lshlrev_b32_e32 v11, 6, v6
	v_add_u32_e32 v5, s30, v12
	s_mov_b32 s30, 0x3fffffc
	v_mul_u32_u24_e32 v13, 0x1200, v6
	v_and_or_b32 v6, v7, s30, v6
	v_and_b32_e32 v7, 15, v130
	v_lshl_or_b32 v6, v6, 6, v7
	v_ashrrev_i32_e32 v7, 31, v6
	v_lshl_add_u64 v[6:7], v[6:7], 4, s[60:61]
	s_mov_b64 s[30:31], 0x40a50000
	s_and_b32 s38, s36, 3
	v_lshl_add_u64 v[68:69], v[6:7], 0, s[30:31]
	s_movk_i32 s30, 0x900
	s_cmp_gt_u32 s36, 3
	v_mad_u32_u24 v6, v8, s30, 0
	v_bfe_u32 v7, v1, 4, 2
	s_cselect_b64 s[30:31], -1, 0
	s_cmp_lt_u32 s36, 4
	s_cselect_b32 s44, 0, 0x4400
	s_lshl_b32 s45, s38, 4
	v_lshlrev_b32_e32 v142, 2, v7
	v_or_b32_e32 v143, s45, v142
	v_or_b32_e32 v146, 1, v143
	v_lshlrev_b32_e32 v18, 2, v146
	v_or_b32_e32 v149, 2, v143
	s_add_i32 s44, s44, 0
	v_add_u32_e32 v147, s2, v18
	v_add_u32_e32 v148, s46, v18
	v_lshlrev_b32_e32 v18, 2, v149
	v_or_b32_e32 v152, 3, v143
	v_mov_b32_e32 v15, s44
	s_and_b32 s44, s39, 0xffffff00
	v_lshlrev_b32_e32 v16, 2, v143
	v_add_u32_e32 v150, s2, v18
	v_add_u32_e32 v151, s46, v18
	v_lshlrev_b32_e32 v18, 2, v152
	s_cmpk_eq_i32 s44, 0x100
	v_add_u32_e32 v144, s2, v16
	v_add_u32_e32 v153, s2, v18
	s_mul_i32 s2, s36, 0x440
	s_cselect_b64 s[84:85], -1, 0
	s_add_i32 s2, s2, 0
	s_add_i32 s2, s2, 0x23400
	s_add_u32 s44, s60, 0x41650000
	v_writelane_b32 v255, s44, 31
	s_addc_u32 s44, s61, 0
; DI float fexp(float x) { return __builtin_amdgcn_exp2f(x * 1.4426950408889634f); }
; DI float softplus(float x) { return fmaxf(x, 0.f) + flog(1.f + fexp(-fabsf(x))); }
;     ...
;         float g = -fexp(F.in[16][layer * 6 + h]) * softplus(pba[6 + h] + F.in[17][layer * 6 + h]);
;     ...
;         if (wave == 0 && !(variant & 1)) {
;             const int bk = lane >> 4, c = lane & 15; const float fc = (float)c;
;             float t[16];
; #pragma unroll
;             for (int i = 0; i < 16; ++i) {
;                 float acc = fmaxf(0.f, 1.f - fabsf(fc - (float)i));
	v_and_b32_e32 v141, 15, v1
	v_writelane_b32 v255, s44, 32
	s_add_u32 s44, s60, 0x42250000
	v_or_b32_e32 v14, s45, v141
	v_writelane_b32 v255, s44, 33
	s_addc_u32 s44, s61, 0
	v_add_u32_e32 v20, -1, v141
	v_mad_u32_u24 v14, v14, s7, v15
	v_and_b32_e32 v15, 48, v1
	v_writelane_b32 v255, s44, 34
	s_movk_i32 s44, 0x640
	v_cvt_f32_i32_e32 v20, v20
	v_add_u32_e32 v154, s46, v18
	v_cmp_gt_i32_e64 s[56:57], s44, v1
	v_lshlrev_b32_e32 v18, 2, v15
	v_lshlrev_b32_e32 v19, 2, v141
	v_readlane_b32 s45, v254, 62
	s_add_i32 s44, 0, 0x16000
	v_add_u32_e32 v157, s44, v18
	v_add3_u32 v156, s45, v18, v19
	v_cvt_f32_ubyte0_e32 v18, v141
	v_sub_f32_e32 v18, 1.0, v18
	v_max_f32_e32 v158, 0, v18
	v_sub_f32_e64 v18, 1.0, |v20|
	v_add_u32_e32 v20, -2, v141
	v_cvt_f32_i32_e32 v20, v20
	v_add_u32_e32 v21, -3, v141
	v_cvt_f32_i32_e32 v21, v21
	v_max_f32_e32 v160, 0, v18
	v_sub_f32_e64 v18, 1.0, |v20|
	v_add_u32_e32 v20, -4, v141
	v_max_f32_e32 v161, 0, v18
	v_sub_f32_e64 v18, 1.0, |v21|
	v_cvt_f32_i32_e32 v20, v20
	v_add_u32_e32 v21, -5, v141
	v_cvt_f32_i32_e32 v21, v21
	v_max_f32_e32 v162, 0, v18
	v_sub_f32_e64 v18, 1.0, |v20|
	v_add_u32_e32 v20, -6, v141
	v_max_f32_e32 v163, 0, v18
	v_sub_f32_e64 v18, 1.0, |v21|
	v_cvt_f32_i32_e32 v20, v20
	v_add_u32_e32 v21, -7, v141
	v_cvt_f32_i32_e32 v21, v21
	v_max_f32_e32 v164, 0, v18
	v_sub_f32_e64 v18, 1.0, |v20|
	v_add_u32_e32 v20, -8, v141
	v_max_f32_e32 v165, 0, v18
	v_sub_f32_e64 v18, 1.0, |v21|
	v_cvt_f32_i32_e32 v20, v20
	v_add_u32_e32 v21, -9, v141
	v_cvt_f32_i32_e32 v21, v21
	v_max_f32_e32 v166, 0, v18
	v_sub_f32_e64 v18, 1.0, |v20|
	v_add_u32_e32 v20, -10, v141
	v_max_f32_e32 v167, 0, v18
	v_sub_f32_e64 v18, 1.0, |v21|
	v_cvt_f32_i32_e32 v20, v20
	v_add_u32_e32 v21, -11, v141
	v_cvt_f32_i32_e32 v21, v21
	v_max_f32_e32 v168, 0, v18
	v_sub_f32_e64 v18, 1.0, |v20|
	v_add_u32_e32 v20, -12, v141
	v_max_f32_e32 v169, 0, v18
	v_sub_f32_e64 v18, 1.0, |v21|
	v_cvt_f32_i32_e32 v20, v20
	v_add_u32_e32 v21, -13, v141
	v_cvt_f32_i32_e32 v21, v21
	v_max_f32_e32 v170, 0, v18
	v_sub_f32_e64 v18, 1.0, |v20|
	v_add_u32_e32 v20, -14, v141
	v_max_f32_e32 v171, 0, v18
	v_sub_f32_e64 v18, 1.0, |v21|
	v_cvt_f32_i32_e32 v20, v20
	v_add_u32_e32 v21, -15, v141
	v_cvt_f32_i32_e32 v21, v21
	v_max_f32_e32 v172, 0, v18
	v_sub_f32_e64 v18, 1.0, |v20|
	v_max_f32_e32 v173, 0, v18
	v_sub_f32_e64 v18, 1.0, |v21|
	v_max_f32_e32 v174, 0, v18
	v_or_b32_e32 v18, 15, v71
	v_add_u32_e32 v176, s2, v19
	s_lshl_b32 s2, s36, 4
	v_mul_u32_u24_e32 v175, 0x110, v18
	s_and_b32 s47, s39, 0xffffffc0
	v_bfe_u32 v18, v1, 1, 2
	v_ashrrev_i32_e32 v20, 7, v1
	s_sub_i32 s2, s2, 64
	s_add_i32 s44, s47, s45
	s_sub_i32 s75, 4, s36
	v_cmp_gt_i32_e64 s[58:59], v18, v20
	s_lshl_b32 s95, s36, 3
	v_or_b32_e32 v20, s2, v141
	v_add_u32_e32 v72, s44, v19
	v_mul_lo_u32 v18, v130, s91
	v_readlane_b32 s44, v254, 63
	v_mul_lo_u32 v20, v20, s91
	v_mov_b32_e32 v21, s39
	s_movk_i32 s2, 0xffc0
	s_add_u32 s39, s60, 0x42850000
	v_add_u32_e32 v18, s44, v18
	v_add_u32_e32 v20, s44, v20
	v_add_u32_e32 v178, s44, v15
	v_bfi_b32 v179, s2, v21, v1
	s_addc_u32 s44, s61, 0
	s_mul_i32 s2, s36, 0x1140
	v_subrev_u32_e32 v155, 64, v1
	v_add_u32_e32 v10, s45, v10
	s_add_u32 s45, s60, 0x3fe50000
	v_mov_b32_e32 v1, s2
	s_mul_i32 s2, s36, 0x1100
	v_add_u32_e32 v145, s46, v16
	v_mul_u32_u24_e32 v177, 0x110, v7
	s_addc_u32 s46, s61, 0
	v_mad_u32_u24 v1, v141, s7, v1
	s_add_i32 s2, s47, s2
	v_lshlrev_b32_e32 v9, 4, v8
	v_mul_u32_u24_e32 v17, 0x90, v143
	v_mul_u32_u24_e32 v16, 0x110, v143
	v_mul_u32_u24_e32 v7, 0x44, v7
	v_lshlrev_b32_e32 v8, 5, v8
	v_or_b32_e32 v188, v1, v142
	v_add3_u32 v189, s2, v177, v19
	s_addk_i32 s47, 0xff00
	v_mul_u32_u24_e32 v1, 0x90, v141
	v_readlane_b32 s2, v255, 0
	v_lshlrev_b32_e32 v74, 2, v0
	v_add_u32_e32 v0, 0, v3
	v_ashrrev_i32_e32 v67, 31, v66
	v_cmp_eq_u32_e64 s[42:43], 0, v71
	v_cmp_gt_u32_e64 s[52:53], 32, v71
	v_or_b32_e32 v131, 0x1800, v9
	v_add_u32_e32 v132, -3, v130
	v_add_u32_e32 v70, 0, v15
	v_mul_u32_u24_e32 v159, 0x110, v15
	v_or_b32_e32 v180, v16, v19
	v_lshl_or_b32 v181, v141, 1, v17
	v_or_b32_e32 v186, 0x1ed00, v19
	v_mad_u32_u24 v187, v141, s7, v15
	v_or_b32_e32 v190, s47, v71
	v_add3_u32 v191, v1, v15, s2
	v_add_u32_e32 v192, 0x25600, v0
	v_add_u32_e32 v193, v4, v13
	v_add_u32_e32 v194, v5, v13
	v_add_u32_e32 v195, v6, v12
	v_add_u32_e32 v196, v14, v15
	v_add_u32_e32 v197, v176, v7
	v_add_u32_e32 v198, v10, v8
	v_add_u32_e32 v199, v18, v9
	v_add_u32_e32 v200, v20, v15
	v_add_u32_e32 v201, v2, v11
	v_readlane_b32 s47, v252, 2
	s_load_dwordx2 s[98:99], s[82:83], 0x80
	s_load_dwordx2 s[100:101], s[82:83], 0x88
	s_waitcnt lgkmcnt(0)
	s_branch .LBB0_715

; #define GAS __attribute__((address_space(1)))
; #define LAS __attribute__((address_space(3)))
; #define LDS_WAIT() asm volatile("s_waitcnt lgkmcnt(0)" ::: "memory")
; DI float fexp(float x) { return __builtin_amdgcn_exp2f(x * 1.4426950408889634f); }
; DI float sigm(float x) { return frcp(1.f + fexp(-x)); }
; DI float softplus(float x) { return fmaxf(x, 0.f) + flog(1.f + fexp(-fabsf(x))); }
;     ...
;     if (tid < 384) { const int j = tid / 96, i96 = tid % 96, seg = i96 >> 5, c4 = (i96 & 31) * 4;
;         const f32x4 cwv = *(const GAS f32x4*)(F.in[15] + ((size_t)layer * 4 + j) * 2304 + seg * 768 + h * 128 + c4);
;         *(LAS f32x4*)(L + gp::CW + (j * 384 + seg * 128 + c4) * 4) = cwv; }
;     if (wave == 0) {
;         const float* pba = PBA + (m0 + lane) * 16;
;         const float beta = sigm(pba[h]);
;         float g = -fexp(F.in[16][layer * 6 + h]) * softplus(pba[6 + h] + F.in[17][layer * 6 + h]);
; #pragma unroll
;         for (int o = 1; o < 64; o <<= 1) { const float v = __shfl_up(g, o); if (lane >= o) g += v; }
;         const float blast = __shfl(g, 63);
;         BETA[lane] = beta; BC[lane] = g;
;         if (lane == 0) { BC[64] = blast; ((float*)(F.ws + WS_GE))[cidx] = fexp(blast); }
;     }
;     LDS_WAIT(); __syncthreads();
;     const float blast = BC[64];
;         const int t2 = tid >> 3, c02 = 16 * (tid & 7);
;         const int pcol2 = PC_V + h * 128 + c02, wch2 = 1536 + h * 128 + c02;
;         float av[16];
; #pragma unroll
;         for (int c = 0; c < 16; ++c) av[c] = 0.f;
;         v4u xv[4][2];
; #pragma unroll
;         for (int j = 0; j < 4; ++j) {
;             const int tt = t0 + t2 - 3 + j;
;             if (tt >= 0) { const bf16* src = P + ((size_t)b * SEQ + tt) * NP + pcol2; xv[j][0] = *(const GAS v4u*)src; xv[j][1] = *(const GAS v4u*)(src + 8); }
;         }
;     ...
; #pragma unroll
;         for (int j = 0; j < 4; ++j) {
;             const int tt = t0 + t - 3 + j;
;             if (tt >= 0) { const bf16* src = P + ((size_t)b * SEQ + tt) * NP + pcol;
; #pragma unroll
;                 for (int q4 = 0; q4 < 4; ++q4) xq[j][q4] = *(const GAS v4u*)(src + 8 * q4); }
;         }
.LBB0_715:
	s_ashr_i32 s62, s47, 6
	s_mul_hi_i32 s2, s62, 0x2aaaaaab
	s_lshr_b32 s48, s2, 31
	s_add_i32 s64, s2, s48
	s_mul_i32 s2, s64, 6
	s_sub_i32 s60, s62, s2
	s_ashr_i32 s63, s62, 31
	s_and_b32 s48, s47, 63
	s_ashr_i32 s65, s64, 31
	s_lshl_b64 s[76:77], s[62:63], 6
	s_lshl_b32 s2, s48, 6
	s_lshl_b64 s[86:87], s[64:65], 12
	s_or_b32 s76, s76, s48
	s_load_dwordx2 s[48:49], s[82:83], 0x78
	s_lshl_b32 s63, s60, 7
	v_add_u32_e32 v98, s63, v131
	v_mov_b32_e32 v99, v97
	v_lshl_add_u64 v[248:249], v[98:99], 1, s[0:1]
	v_add_u32_e32 v98, s63, v137
	v_mov_b32_e32 v99, v97
	v_add_u32_e32 v233, s2, v132
	v_lshl_add_u64 v[62:63], v[98:99], 1, s[0:1]
	v_add_u32_e32 v242, s86, v233
	v_cmp_lt_i32_e32 vcc, -1, v233
	s_and_b64 exec, exec, vcc
	v_mad_u64_u32 v[250:251], vcc, v242, s97, v[62:63]
	v_mad_u64_u32 v[246:247], vcc, v242, s97, v[248:249]
	global_load_dwordx4 v[24:27], v[246:247], off offset:16
	global_load_dwordx4 v[28:31], v[246:247], off
	global_load_dwordx4 v[54:57], v[250:251], off offset:48
	global_load_dwordx4 v[58:61], v[250:251], off offset:32
	global_load_dwordx4 v[102:105], v[250:251], off offset:16
	global_load_dwordx4 v[106:109], v[250:251], off
	s_mov_b64 exec, -1
	v_add_u32_e32 v242, 1, v242
	v_cmp_lt_i32_e32 vcc, -2, v233
	s_and_b64 exec, exec, vcc
	v_mad_u64_u32 v[250:251], vcc, v242, s97, v[62:63]
	v_mad_u64_u32 v[246:247], vcc, v242, s97, v[248:249]
	global_load_dwordx4 v[16:19], v[246:247], off offset:16
	global_load_dwordx4 v[20:23], v[246:247], off
	global_load_dwordx4 v[110:113], v[250:251], off offset:48
	global_load_dwordx4 v[114:117], v[250:251], off offset:32
	global_load_dwordx4 v[118:121], v[250:251], off offset:16
	global_load_dwordx4 v[122:125], v[250:251], off
	s_mov_b64 exec, -1
	v_add_u32_e32 v242, 1, v242
	v_cmp_lt_i32_e32 vcc, -3, v233
	s_and_b64 exec, exec, vcc
	v_mad_u64_u32 v[250:251], vcc, v242, s97, v[62:63]
	v_mad_u64_u32 v[246:247], vcc, v242, s97, v[248:249]
	global_load_dwordx4 v[4:7], v[246:247], off offset:16
	global_load_dwordx4 v[12:15], v[246:247], off
	global_load_dwordx4 v[126:129], v[250:251], off offset:48
	global_load_dwordx4 v[202:205], v[250:251], off offset:32
	global_load_dwordx4 v[206:209], v[250:251], off offset:16
	global_load_dwordx4 v[210:213], v[250:251], off
	s_mov_b64 exec, -1
	v_add_u32_e32 v242, 1, v242
	v_cmp_lt_i32_e32 vcc, -4, v233
	s_and_b64 exec, exec, vcc
	v_mad_u64_u32 v[250:251], vcc, v242, s97, v[62:63]
	v_mad_u64_u32 v[246:247], vcc, v242, s97, v[248:249]
	global_load_dwordx4 v[0:3], v[246:247], off offset:16
	global_load_dwordx4 v[8:11], v[246:247], off
	global_load_dwordx4 v[214:217], v[250:251], off offset:48
	global_load_dwordx4 v[218:221], v[250:251], off offset:32
	global_load_dwordx4 v[222:225], v[250:251], off offset:16
	global_load_dwordx4 v[234:237], v[250:251], off
	s_mov_b64 exec, -1
	s_and_saveexec_b64 s[66:67], s[40:41]
	s_cbranch_execz .LBB0_717
	v_mov_b32_e32 v75, v97
	s_waitcnt lgkmcnt(0)
	v_lshl_add_u64 v[250:251], s[48:49], 0, v[64:65]
	s_lshl_b32 s48, s60, 7
	v_lshl_add_u64 v[250:251], v[66:67], 2, v[250:251]
	s_ashr_i32 s49, s48, 31
	v_lshl_add_u64 v[250:251], s[48:49], 2, v[250:251]
	v_lshl_add_u64 v[250:251], v[250:251], 0, v[74:75]
	global_load_dwordx4 v[238:241], v[250:251], off
.LBB0_717:
	s_or_b64 exec, exec, s[66:67]
	s_waitcnt lgkmcnt(0)
	s_andn2_b64 vcc, exec, s[80:81]
	s_cbranch_vccnz .LBB0_721
	v_readlane_b32 s48, v255, 17
	s_mul_i32 s48, s48, 6
	s_add_i32 s48, s60, s48
	s_ashr_i32 s49, s48, 31
	v_or_b32_e32 v62, s2, v71
	s_ashr_i32 s61, s60, 31
	s_lshl_b64 s[48:49], s[48:49], 2
	v_or_b32_e32 v62, s86, v62
	v_mov_b32_e32 v63, s87
	s_waitcnt lgkmcnt(0)
	s_add_u32 s62, s98, s48
	v_lshlrev_b64 v[62:63], 6, v[62:63]
	s_addc_u32 s63, s99, s49
	v_lshl_add_u64 v[62:63], s[78:79], 0, v[62:63]
	s_add_u32 s48, s100, s48
	v_lshl_add_u64 v[62:63], s[60:61], 2, v[62:63]
	s_addc_u32 s49, s101, s49
	flat_load_dword v98, v[62:63]
	global_load_dword v99, v97, s[62:63]
	v_and_b32_e32 v233, 64, v228
	flat_load_dword v62, v[62:63] offset:24
	v_add_u32_e32 v242, -1, v228
	global_load_dword v63, v97, s[48:49]
	s_mov_b32 s48, 0xbfb8aa3b
	v_cmp_lt_i32_e32 vcc, v242, v233
	s_waitcnt vmcnt(0) lgkmcnt(0)
	v_mul_f32_e32 v98, 0xbfb8aa3b, v98
	v_mul_f32_e32 v99, 0x3fb8aa3b, v99
	v_exp_f32_e32 v99, v99
	v_cndmask_b32_e32 v242, v242, v228, vcc
	v_lshlrev_b32_e32 v242, 2, v242
	v_add_f32_e32 v62, v62, v63
	v_max_f32_e32 v63, 0, v62
	v_mul_f32_e64 v62, |v62|, s48
	v_exp_f32_e32 v62, v62
	v_readlane_b32 s48, v255, 21
	v_readlane_b32 s49, v255, 22
	v_exp_f32_e32 v98, v98
	v_add_f32_e32 v62, 1.0, v62
	v_log_f32_e32 v62, v62
	v_add_f32_e32 v98, 1.0, v98
	v_rcp_f32_e32 v98, v98
	v_fmac_f32_e32 v63, 0x3f317218, v62
	v_mul_f32_e64 v62, v63, -v99
	ds_bpermute_b32 v242, v242, v62
	s_waitcnt lgkmcnt(0)
	v_fma_f32 v63, v63, -v99, v242
	v_cndmask_b32_e64 v62, v63, v62, s[42:43]
	v_add_u32_e32 v63, -2, v228
	v_cmp_lt_i32_e32 vcc, v63, v233
	s_nop 1
	v_cndmask_b32_e32 v63, v63, v228, vcc
	v_lshlrev_b32_e32 v63, 2, v63
	ds_bpermute_b32 v63, v63, v62
	s_waitcnt lgkmcnt(0)
	v_add_f32_e32 v63, v62, v63
	v_cndmask_b32_e64 v62, v63, v62, s[48:49]
	v_add_u32_e32 v63, -4, v228
	v_cmp_lt_i32_e32 vcc, v63, v233
	v_readlane_b32 s48, v255, 23
	v_readlane_b32 s49, v255, 24
	v_cndmask_b32_e32 v63, v63, v228, vcc
	v_lshlrev_b32_e32 v63, 2, v63
	ds_bpermute_b32 v63, v63, v62
	s_waitcnt lgkmcnt(0)
	v_add_f32_e32 v63, v62, v63
	v_cndmask_b32_e64 v62, v63, v62, s[48:49]
	v_add_u32_e32 v63, -8, v228
	v_cmp_lt_i32_e32 vcc, v63, v233
	v_readlane_b32 s48, v255, 25
	v_readlane_b32 s49, v255, 26
	v_cndmask_b32_e32 v63, v63, v228, vcc
	v_lshlrev_b32_e32 v63, 2, v63
	ds_bpermute_b32 v63, v63, v62
	s_waitcnt lgkmcnt(0)
	v_add_f32_e32 v63, v62, v63
	v_cndmask_b32_e64 v62, v63, v62, s[48:49]
	v_add_u32_e32 v63, -16, v228
	v_cmp_lt_i32_e32 vcc, v63, v233
	v_readlane_b32 s48, v255, 27
	v_readlane_b32 s49, v255, 28
	v_cndmask_b32_e32 v63, v63, v228, vcc
	v_lshlrev_b32_e32 v63, 2, v63
	ds_bpermute_b32 v63, v63, v62
	s_waitcnt lgkmcnt(0)
	v_add_f32_e32 v63, v62, v63
	v_cndmask_b32_e64 v62, v63, v62, s[48:49]
	v_subrev_u32_e32 v63, 32, v228
	v_cmp_lt_i32_e32 vcc, v63, v233
	s_nop 1
	v_cndmask_b32_e32 v63, v63, v228, vcc
	v_lshlrev_b32_e32 v63, 2, v63
	ds_bpermute_b32 v63, v63, v62
	s_waitcnt lgkmcnt(0)
	v_add_f32_e32 v63, v62, v63
	v_cndmask_b32_e64 v63, v63, v62, s[52:53]
	v_bfrev_b32_e32 v62, 0.5
	v_lshl_or_b32 v62, v228, 2, v62
	ds_bpermute_b32 v62, v62, v63
	ds_write_b32 v73, v98
	ds_write_b32 v101, v63
	s_and_saveexec_b64 s[62:63], s[42:43]
	s_cbranch_execz .LBB0_720
	s_lshl_b64 s[48:49], s[76:77], 2
	v_readlane_b32 s50, v255, 29
	s_waitcnt lgkmcnt(2)
	v_mul_f32_e32 v63, 0x3fb8aa3b, v62
	s_add_u32 s48, s50, s48
	v_readlane_b32 s50, v255, 30
	v_exp_f32_e32 v98, v63
	s_addc_u32 s49, s50, s49
	v_readlane_b32 s50, v255, 1
	s_nop 1
	v_mov_b32_e32 v63, s50
	ds_write_b32 v63, v62
	v_mov_b64_e32 v[62:63], s[48:49]
	flat_store_dword v[62:63], v98

; #define GAS __attribute__((address_space(1)))
; #define LAS __attribute__((address_space(3)))
; #define LDS_WAIT() asm volatile("s_waitcnt lgkmcnt(0)" ::: "memory")
; DI float bflo(unsigned w) { return __uint_as_float(w << 16); }
; DI float bfhi(unsigned w) { return __uint_as_float(w & 0xffff0000u); }
;     ...
;         *(LAS f32x4*)(L + gp::CW + (j * 384 + seg * 128 + c4) * 4) = cwv; }
;     ...
;     LDS_WAIT(); __syncthreads();
;     const float blast = BC[64];
;         const int t2 = tid >> 3, c02 = 16 * (tid & 7);
;         const int pcol2 = PC_V + h * 128 + c02, wch2 = 1536 + h * 128 + c02;
;         float av[16];
; #pragma unroll
;         for (int c = 0; c < 16; ++c) av[c] = 0.f;
;         v4u xv[4][2];
; #pragma unroll
;         for (int j = 0; j < 4; ++j) {
;             const int tt = t0 + t2 - 3 + j;
;             if (tt >= 0) { const bf16* src = P + ((size_t)b * SEQ + tt) * NP + pcol2; xv[j][0] = *(const GAS v4u*)src; xv[j][1] = *(const GAS v4u*)(src + 8); }
;         }
; #pragma unroll
;         for (int j = 0; j < 4; ++j) {
;             const int tt = t0 + t2 - 3 + j;
;             if (tt >= 0) {
;                 const LAS float* wp = (const LAS float*)(L + gp::CW) + j * 384 + 256 + c02;
; #pragma unroll
;                 for (int q4 = 0; q4 < 2; ++q4) {
;                     const v4u x = xv[j][q4]; const f32x4 w0 = *(const LAS f32x4*)(wp + 8 * q4), w1 = *(const LAS f32x4*)(wp + 8 * q4 + 4);
;                     av[8 * q4 + 0] += bflo(x.x) * w0.x; av[8 * q4 + 1] += bfhi(x.x) * w0.y; av[8 * q4 + 2] += bflo(x.y) * w0.z; av[8 * q4 + 3] += bfhi(x.y) * w0.w;
;                     av[8 * q4 + 4] += bflo(x.z) * w1.x; av[8 * q4 + 5] += bfhi(x.z) * w1.y; av[8 * q4 + 6] += bflo(x.w) * w1.z; av[8 * q4 + 7] += bfhi(x.w) * w1.w;
;                 }
;             }
;         }
.LBB0_721:
	s_andn2_b64 vcc, exec, s[80:81]
	s_cbranch_vccz .Lgp_w0
	s_waitcnt vmcnt(0)
.Lgp_w0:
	s_and_b64 exec, exec, s[40:41]
	ds_write_b128 v192, v[238:241]
	s_mov_b64 exec, -1
	v_readlane_b32 s48, v255, 1
	s_waitcnt lgkmcnt(0)
	s_waitcnt lgkmcnt(0)
	s_barrier
	v_mov_b32_e32 v62, s48
	ds_read_b32 v75, v62
	s_lshl_b32 s48, s60, 7
	v_add_u32_e32 v96, s48, v131
	v_add_u32_e32 v32, s2, v132
	v_mov_b32_e32 v33, v97
	v_mov_b32_e32 v35, v97
	v_mov_b32_e32 v95, v97
	v_mov_b32_e32 v93, v97
	v_cmp_lt_i32_e64 s[70:71], -1, v32
	v_add_u32_e32 v34, 1, v32
	v_cmp_lt_i32_e64 s[68:69], -2, v32
	v_add_u32_e32 v94, 2, v32
	v_cmp_lt_i32_e64 s[66:67], -3, v32
	v_add_u32_e32 v92, s2, v130
	v_cmp_lt_i32_e32 vcc, -1, v92
	v_mov_b32_e32 v96, v97
	v_cmp_lt_i32_e64 s[64:65], 2, v92
	v_mov_b64_e32 v[76:77], v[96:97]
	v_mov_b64_e32 v[78:79], v[96:97]
	v_mov_b64_e32 v[80:81], v[96:97]
	v_mov_b64_e32 v[82:83], v[96:97]
	v_mov_b64_e32 v[84:85], v[96:97]
	v_mov_b64_e32 v[86:87], v[96:97]
	v_mov_b64_e32 v[88:89], v[96:97]
	v_mov_b64_e32 v[90:91], v[96:97]
	s_and_saveexec_b64 s[60:61], s[64:65]
	s_cbranch_execz .LBB0_733
	ds_read_b128 v[36:39], v133
	ds_read_b128 v[40:43], v133 offset:16
	ds_read_b128 v[44:47], v133 offset:32
	ds_read_b128 v[48:51], v133 offset:48
	s_waitcnt vmcnt(0)
	v_and_b32_e32 v53, 0xffff0000, v28
	v_lshlrev_b32_e32 v52, 16, v28
	s_waitcnt lgkmcnt(3)
	v_pk_fma_f32 v[90:91], v[36:37], v[52:53], 0 op_sel_hi:[1,1,0]
	v_and_b32_e32 v37, 0xffff0000, v29
	v_lshlrev_b32_e32 v36, 16, v29
	v_and_b32_e32 v29, 0xffff0000, v30
	v_lshlrev_b32_e32 v28, 16, v30
	s_waitcnt lgkmcnt(2)
	v_pk_fma_f32 v[86:87], v[40:41], v[28:29], 0 op_sel_hi:[1,1,0]
	v_and_b32_e32 v29, 0xffff0000, v31
	v_lshlrev_b32_e32 v28, 16, v31
	v_pk_fma_f32 v[84:85], v[42:43], v[28:29], 0 op_sel_hi:[1,1,0]
	v_and_b32_e32 v29, 0xffff0000, v24
	v_lshlrev_b32_e32 v28, 16, v24
	s_waitcnt lgkmcnt(1)
	v_pk_fma_f32 v[82:83], v[44:45], v[28:29], 0 op_sel_hi:[1,1,0]
	v_and_b32_e32 v29, 0xffff0000, v25
	v_lshlrev_b32_e32 v28, 16, v25
	v_and_b32_e32 v25, 0xffff0000, v26
	v_lshlrev_b32_e32 v24, 16, v26
	s_waitcnt lgkmcnt(0)
	v_pk_fma_f32 v[78:79], v[48:49], v[24:25], 0 op_sel_hi:[1,1,0]
	v_and_b32_e32 v25, 0xffff0000, v27
	v_lshlrev_b32_e32 v24, 16, v27
	v_pk_fma_f32 v[88:89], v[38:39], v[36:37], 0 op_sel_hi:[1,1,0]
	v_pk_fma_f32 v[80:81], v[46:47], v[28:29], 0 op_sel_hi:[1,1,0]
	v_pk_fma_f32 v[76:77], v[50:51], v[24:25], 0 op_sel_hi:[1,1,0]
	s_or_b64 exec, exec, s[60:61]
	v_cmp_lt_i32_e64 s[62:63], 1, v92
	s_and_saveexec_b64 s[60:61], s[62:63]
	s_cbranch_execnz .LBB0_734

; #define GAS __attribute__((address_space(1)))
; DI void hgrn_prep_job(const Frame& F, int job, int layer, LAS unsigned char* scr) {
;     ...
;         const int dk = 64 * half + lane;
;         const float lb = ((const GAS float*)lbs)[dk];
;         const GAS bf16* pq = (const GAS bf16*)(P + m0 * NP + PB_Q + h * 128 + dk); const GAS bf16* pf = (const GAS bf16*)(P + m0 * NP + PB_F + h * 128 + dk); const GAS bf16* pv = (const GAS bf16*)(P + m0 * NP + PB_I + h * 128 + dk);
;         unsigned short ve[32];
; #pragma unroll
;         for (int t = 0; t < 32; ++t) ve[t] = pv[(size_t)t * NP];
;         float bq[32], kv[32], qv[32]; float bsum = 0.f;
;         unsigned short qe[32], fe[32];
; #pragma unroll
;         for (int t = 0; t < 32; ++t) { qe[t] = pq[(size_t)t * NP]; fe[t] = pf[(size_t)t * NP]; }
.LBB0_810:
	v_or_b32_e32 v96, s0, v48
	v_lshlrev_b64 v[6:7], 1, v[96:97]
	v_lshl_add_u64 v[8:9], s[70:71], 0, v[6:7]
	v_lshl_add_u64 v[14:15], s[66:67], 0, v[6:7]
	v_lshl_add_u64 v[12:13], s[68:69], 0, v[6:7]
	s_cmp_eq_u64 s[82:83], 0
	s_cbranch_scc1 .Lhg_skip_top
	v_mov_b32_e32 v139, v6
	global_load_ushort v141, v139, s[66:67] offset:3072
	global_load_ushort v173, v139, s[68:69]
	v_add_u32_e32 v140, 0x3c00, v139
	global_load_ushort v142, v140, s[66:67] offset:3072
	global_load_ushort v174, v140, s[68:69]
	v_add_u32_e32 v140, 0x7800, v139
	global_load_ushort v143, v140, s[66:67] offset:3072
	global_load_ushort v175, v140, s[68:69]
	v_add_u32_e32 v140, 0xb400, v139
	global_load_ushort v144, v140, s[66:67] offset:3072
	global_load_ushort v176, v140, s[68:69]
	v_add_u32_e32 v140, 0xf000, v139
	global_load_ushort v145, v140, s[66:67] offset:3072
	global_load_ushort v177, v140, s[68:69]
	v_add_u32_e32 v140, 0x12c00, v139
	global_load_ushort v146, v140, s[66:67] offset:3072
	global_load_ushort v178, v140, s[68:69]
	v_add_u32_e32 v140, 0x16800, v139
	global_load_ushort v147, v140, s[66:67] offset:3072
	global_load_ushort v179, v140, s[68:69]
	v_add_u32_e32 v140, 0x1a400, v139
	global_load_ushort v148, v140, s[66:67] offset:3072
	global_load_ushort v180, v140, s[68:69]
	v_add_u32_e32 v140, 0x1e000, v139
	global_load_ushort v149, v140, s[66:67] offset:3072
	global_load_ushort v181, v140, s[68:69]
	v_add_u32_e32 v140, 0x21c00, v139
	global_load_ushort v150, v140, s[66:67] offset:3072
	global_load_ushort v182, v140, s[68:69]
	v_add_u32_e32 v140, 0x25800, v139
	global_load_ushort v151, v140, s[66:67] offset:3072
	global_load_ushort v183, v140, s[68:69]
	v_add_u32_e32 v140, 0x29400, v139
	global_load_ushort v152, v140, s[66:67] offset:3072
	global_load_ushort v186, v140, s[68:69]
	v_add_u32_e32 v140, 0x2d000, v139
	global_load_ushort v153, v140, s[66:67] offset:3072
	global_load_ushort v187, v140, s[68:69]
	v_add_u32_e32 v140, 0x30c00, v139
	global_load_ushort v154, v140, s[66:67] offset:3072
	global_load_ushort v188, v140, s[68:69]
	v_add_u32_e32 v140, 0x34800, v139
	global_load_ushort v155, v140, s[66:67] offset:3072
	global_load_ushort v189, v140, s[68:69]
	v_add_u32_e32 v140, 0x38400, v139
	global_load_ushort v156, v140, s[66:67] offset:3072
	global_load_ushort v190, v140, s[68:69]
	v_add_u32_e32 v140, 0x3c000, v139
	global_load_ushort v157, v140, s[66:67] offset:3072
	global_load_ushort v191, v140, s[68:69]
	v_add_u32_e32 v140, 0x3fc00, v139
	global_load_ushort v158, v140, s[66:67] offset:3072
	global_load_ushort v192, v140, s[68:69]
	v_add_u32_e32 v140, 0x43800, v139
	global_load_ushort v159, v140, s[66:67] offset:3072
	global_load_ushort v193, v140, s[68:69]
	v_add_u32_e32 v140, 0x47400, v139
	global_load_ushort v160, v140, s[66:67] offset:3072
	global_load_ushort v194, v140, s[68:69]
	v_add_u32_e32 v140, 0x4b000, v139
	global_load_ushort v161, v140, s[66:67] offset:3072
	global_load_ushort v195, v140, s[68:69]
	v_add_u32_e32 v140, 0x4ec00, v139
	global_load_ushort v162, v140, s[66:67] offset:3072
	global_load_ushort v196, v140, s[68:69]
	v_add_u32_e32 v140, 0x52800, v139
	global_load_ushort v163, v140, s[66:67] offset:3072
	global_load_ushort v197, v140, s[68:69]
	v_add_u32_e32 v140, 0x56400, v139
	global_load_ushort v164, v140, s[66:67] offset:3072
	global_load_ushort v198, v140, s[68:69]
	v_add_u32_e32 v140, 0x5a000, v139
	global_load_ushort v165, v140, s[66:67] offset:3072
	global_load_ushort v199, v140, s[68:69]
	v_add_u32_e32 v140, 0x5dc00, v139
	global_load_ushort v166, v140, s[66:67] offset:3072
	global_load_ushort v200, v140, s[68:69]
	v_add_u32_e32 v140, 0x61800, v139
	global_load_ushort v167, v140, s[66:67] offset:3072
	global_load_ushort v201, v140, s[68:69]
	v_add_u32_e32 v140, 0x65400, v139
	global_load_ushort v168, v140, s[66:67] offset:3072
	global_load_ushort v202, v140, s[68:69]
	v_add_u32_e32 v140, 0x69000, v139
	global_load_ushort v169, v140, s[66:67] offset:3072
	global_load_ushort v203, v140, s[68:69]
	v_add_u32_e32 v140, 0x6cc00, v139
	global_load_ushort v170, v140, s[66:67] offset:3072
	global_load_ushort v204, v140, s[68:69]
	v_add_u32_e32 v140, 0x70800, v139
	global_load_ushort v171, v140, s[66:67] offset:3072
	global_load_ushort v205, v140, s[68:69]
	v_add_u32_e32 v140, 0x74400, v139
	global_load_ushort v172, v140, s[66:67] offset:3072
	global_load_ushort v206, v140, s[68:69]
	v_lshlrev_b32_e32 v208, 1, v139
	global_load_dword v207, v208, s[56:57]
; DI float bf2f(unsigned v) { return __uint_as_float(v << 16); }
; DI float flog(float x) { return __builtin_amdgcn_logf(x) * 0.6931471805599453f; }
; DI float sigm(float x) { return frcp(1.f + fexp(-x)); }
; DI float silu(float x) { return x * sigm(x); }
; DI void hgrn_prep_job(const Frame& F, int job, int layer, LAS unsigned char* scr) {
;     ...
;         for (int t = 0; t < 32; ++t) ve[t] = pv[(size_t)t * NP];
;         float bq[32], kv[32], qv[32]; float bsum = 0.f;
;         unsigned short qe[32], fe[32];
; #pragma unroll
;         for (int t = 0; t < 32; ++t) { qe[t] = pq[(size_t)t * NP]; fe[t] = pf[(size_t)t * NP]; }
; #pragma unroll
;         for (int t = 0; t < 32; ++t) {
;             const float qx = bf2f(qe[t]), fx = bf2f(fe[t]);
;             const float f = lb + (1.f - lb) * sigm(fx);
;             bsum += flog(f); bq[t] = bsum; kv[t] = 1.f - f; qv[t] = silu(qx);
.Lhg_skip_top:
	v_add_co_u32_e32 v6, vcc, 0x7000, v8
	v_lshlrev_b64 v[10:11], 2, v[96:97]
	s_nop 0
	v_addc_co_u32_e32 v7, vcc, 0, v9, vcc
	global_load_ushort v59, v[6:7], off offset:2048
	v_add_co_u32_e32 v6, vcc, 0xf000, v8
	v_lshl_add_u64 v[4:5], s[56:57], 0, v[10:11]
	s_nop 0
	v_addc_co_u32_e32 v7, vcc, 0, v9, vcc
	s_movk_i32 s0, 0x7000
	global_load_ushort v58, v[8:9], off
	global_load_ushort v60, v[6:7], off
	v_add_co_u32_e32 v6, vcc, s74, v8
	s_nop 0
	v_addc_co_u32_e32 v7, vcc, 0, v9, vcc
	global_load_ushort v61, v[6:7], off offset:2048
	v_add_co_u32_e32 v6, vcc, s89, v8
	v_lshl_add_u32 v119, v96, 1, s31
	s_nop 0
	v_addc_co_u32_e32 v7, vcc, 0, v9, vcc
	global_load_ushort v62, v[6:7], off
	v_add_co_u32_e32 v6, vcc, 0x25000, v8
	s_waitcnt vmcnt(5)
	v_mov_b32_e32 v4, v207
	v_lshlrev_b32_e32 v5, 16, v141
	v_addc_co_u32_e32 v7, vcc, 0, v9, vcc
	global_load_ushort v63, v[6:7], off offset:2048
	v_add_co_u32_e32 v6, vcc, 0x2d000, v8
	s_nop 1
	v_addc_co_u32_e32 v7, vcc, 0, v9, vcc
	global_load_ushort v64, v[6:7], off
	v_add_co_u32_e32 v6, vcc, 0x34000, v8
	s_nop 1
	v_addc_co_u32_e32 v7, vcc, 0, v9, vcc
	global_load_ushort v65, v[6:7], off offset:2048
	v_add_co_u32_e32 v6, vcc, 0x3c000, v8
	s_nop 1
	v_addc_co_u32_e32 v7, vcc, 0, v9, vcc
	global_load_ushort v66, v[6:7], off
	v_add_co_u32_e32 v6, vcc, 0x43000, v8
	s_nop 1
	v_addc_co_u32_e32 v7, vcc, 0, v9, vcc
	global_load_ushort v67, v[6:7], off offset:2048
	v_add_co_u32_e32 v6, vcc, 0x4b000, v8
	s_nop 1
	v_addc_co_u32_e32 v7, vcc, 0, v9, vcc
	global_load_ushort v68, v[6:7], off
	v_add_co_u32_e32 v6, vcc, 0x52000, v8
	s_nop 1
	v_addc_co_u32_e32 v7, vcc, 0, v9, vcc
	global_load_ushort v69, v[6:7], off offset:2048
	v_add_co_u32_e32 v6, vcc, 0x5a000, v8
	s_nop 1
	v_addc_co_u32_e32 v7, vcc, 0, v9, vcc
	global_load_ushort v70, v[6:7], off
	v_add_co_u32_e32 v6, vcc, 0x61000, v8
	s_nop 1
	v_addc_co_u32_e32 v7, vcc, 0, v9, vcc
	global_load_ushort v71, v[6:7], off offset:2048
	v_add_co_u32_e32 v6, vcc, 0x69000, v8
	s_nop 1
	v_addc_co_u32_e32 v7, vcc, 0, v9, vcc
	global_load_ushort v72, v[6:7], off
	v_add_co_u32_e32 v6, vcc, 0x70000, v8
	s_nop 1
	v_addc_co_u32_e32 v7, vcc, 0, v9, vcc
	global_load_ushort v73, v[6:7], off offset:2048
	v_add_co_u32_e32 v18, vcc, s4, v14
	s_nop 0
	v_addc_co_u32_e32 v19, vcc, 0, v15, vcc
	v_sub_f32_e32 v6, 1.0, v4
	v_lshlrev_b32_e32 v7, 16, v173
	v_mul_f32_e32 v7, 0xbfb8aa3b, v7
	v_exp_f32_e32 v7, v7
	s_nop 0
	v_add_f32_e32 v7, 1.0, v7
	v_rcp_f32_e32 v16, v7
	v_mul_f32_e32 v7, 0xbfb8aa3b, v5
	v_exp_f32_e32 v7, v7
	s_nop 0
	v_add_f32_e32 v7, 1.0, v7
	v_rcp_f32_e32 v7, v7
	s_nop 0
	v_mul_f32_e32 v7, v7, v5
	v_add_co_u32_e32 v18, vcc, s14, v12
	v_lshlrev_b32_e32 v5, 16, v142
	v_addc_co_u32_e32 v19, vcc, 0, v13, vcc
	v_mul_f32_e32 v18, 0xbfb8aa3b, v5
	v_exp_f32_e32 v18, v18
	v_lshlrev_b32_e32 v17, 16, v174
	v_add_f32_e32 v18, 1.0, v18
	v_rcp_f32_e32 v18, v18
	v_mul_f32_e32 v17, 0xbfb8aa3b, v17
	v_exp_f32_e32 v17, v17
	v_mul_f32_e32 v5, v18, v5
	v_add_co_u32_e32 v18, vcc, s88, v14
	v_add_f32_e32 v17, 1.0, v17
	s_nop 0
	v_addc_co_u32_e32 v19, vcc, 0, v15, vcc
	v_rcp_f32_e32 v17, v17
	v_lshlrev_b32_e32 v20, 16, v143
	v_add_co_u32_e32 v18, vcc, s0, v12
	s_mov_b32 s0, 0xc000
	s_nop 0
	v_addc_co_u32_e32 v19, vcc, 0, v13, vcc
	v_lshlrev_b32_e32 v18, 16, v175
	v_mul_f32_e32 v18, 0xbfb8aa3b, v18
	v_exp_f32_e32 v18, v18
	s_nop 0
	v_add_f32_e32 v18, 1.0, v18
	v_rcp_f32_e32 v24, v18
	v_mul_f32_e32 v18, 0xbfb8aa3b, v20
	v_exp_f32_e32 v18, v18
	s_nop 0
	v_add_f32_e32 v18, 1.0, v18
	v_rcp_f32_e32 v18, v18
	s_nop 0
	v_mul_f32_e32 v74, v18, v20
	v_add_co_u32_e32 v18, vcc, s0, v14
	s_mov_b32 s0, 0x13000
	s_nop 0
	v_addc_co_u32_e32 v19, vcc, 0, v15, vcc
	v_lshlrev_b32_e32 v20, 16, v144
	v_add_co_u32_e32 v18, vcc, s15, v12
	s_nop 1
	v_addc_co_u32_e32 v19, vcc, 0, v13, vcc
	v_lshlrev_b32_e32 v18, 16, v176
	v_mul_f32_e32 v18, 0xbfb8aa3b, v18
	v_exp_f32_e32 v18, v18
	s_nop 0
	v_add_f32_e32 v18, 1.0, v18
	v_rcp_f32_e32 v25, v18
	v_mul_f32_e32 v18, 0xbfb8aa3b, v20
	v_exp_f32_e32 v18, v18
	s_nop 0
	v_add_f32_e32 v18, 1.0, v18
	v_rcp_f32_e32 v18, v18
	s_nop 0
	v_mul_f32_e32 v76, v18, v20
	v_add_co_u32_e32 v18, vcc, s8, v14
	s_nop 1
	v_addc_co_u32_e32 v19, vcc, 0, v15, vcc
	v_lshlrev_b32_e32 v20, 16, v145
	v_add_co_u32_e32 v18, vcc, s8, v12
	s_nop 1
	v_addc_co_u32_e32 v19, vcc, 0, v13, vcc
	v_mul_f32_e32 v19, 0xbfb8aa3b, v20
	v_exp_f32_e32 v19, v19
	v_lshlrev_b32_e32 v18, 16, v177
	v_add_f32_e32 v19, 1.0, v19
	v_rcp_f32_e32 v19, v19
	v_mul_f32_e32 v18, 0xbfb8aa3b, v18
	v_exp_f32_e32 v18, v18
	v_mul_f32_e32 v75, v19, v20
	v_add_co_u32_e32 v20, vcc, s0, v14
	s_mov_b32 s0, 0x17000
	s_nop 0
	v_addc_co_u32_e32 v21, vcc, 0, v15, vcc
	v_add_co_u32_e32 v20, vcc, s37, v12
	v_add_f32_e32 v18, 1.0, v18
	s_nop 0
	v_addc_co_u32_e32 v21, vcc, 0, v13, vcc
	v_rcp_f32_e32 v18, v18
	v_lshlrev_b32_e32 v22, 16, v146
	v_mul_f32_e32 v20, 0xbfb8aa3b, v22
	v_exp_f32_e32 v20, v20
	v_lshlrev_b32_e32 v19, 16, v178
	v_add_f32_e32 v20, 1.0, v20
	v_rcp_f32_e32 v20, v20
	v_mul_f32_e32 v19, 0xbfb8aa3b, v19
	v_exp_f32_e32 v19, v19
	v_mul_f32_e32 v77, v20, v22
	v_add_co_u32_e32 v20, vcc, s0, v14
	s_mov_b32 s0, 0x1b000
	s_nop 0
	v_addc_co_u32_e32 v21, vcc, 0, v15, vcc
	v_add_f32_e32 v19, 1.0, v19
	v_rcp_f32_e32 v19, v19
	v_lshlrev_b32_e32 v23, 16, v147
	v_add_co_u32_e32 v20, vcc, s74, v12
	s_nop 1
	v_addc_co_u32_e32 v21, vcc, 0, v13, vcc
	v_lshlrev_b32_e32 v20, 16, v179
	v_mul_f32_e32 v20, 0xbfb8aa3b, v20
	v_exp_f32_e32 v20, v20
	s_nop 0
	v_add_f32_e32 v20, 1.0, v20
	v_rcp_f32_e32 v22, v20
	v_mul_f32_e32 v20, 0xbfb8aa3b, v23
	v_exp_f32_e32 v20, v20
	s_nop 0
	v_add_f32_e32 v20, 1.0, v20
	v_rcp_f32_e32 v20, v20
	s_nop 0
	v_mul_f32_e32 v91, v20, v23
; DI float bf2f(unsigned v) { return __uint_as_float(v << 16); }
; DI float flog(float x) { return __builtin_amdgcn_logf(x) * 0.6931471805599453f; }
; DI float sigm(float x) { return frcp(1.f + fexp(-x)); }
; DI float silu(float x) { return x * sigm(x); }
; DI void hgrn_prep_job(const Frame& F, int job, int layer, LAS unsigned char* scr) {
;     ...
;         for (int t = 0; t < 32; ++t) {
;             const float qx = bf2f(qe[t]), fx = bf2f(fe[t]);
;             const float f = lb + (1.f - lb) * sigm(fx);
;             bsum += flog(f); bq[t] = bsum; kv[t] = 1.f - f; qv[t] = silu(qx);
	v_add_co_u32_e32 v20, vcc, s0, v14
	s_mov_b32 s0, 0x25000
	s_nop 0
	v_addc_co_u32_e32 v21, vcc, 0, v15, vcc
	v_lshlrev_b32_e32 v26, 16, v148
	v_add_co_u32_e32 v20, vcc, s5, v12
	s_nop 1
	v_addc_co_u32_e32 v21, vcc, 0, v13, vcc
	v_lshlrev_b32_e32 v20, 16, v180
	v_mul_f32_e32 v20, 0xbfb8aa3b, v20
	v_exp_f32_e32 v20, v20
	s_nop 0
	v_add_f32_e32 v20, 1.0, v20
	v_rcp_f32_e32 v23, v20
	v_mul_f32_e32 v20, 0xbfb8aa3b, v26
	v_exp_f32_e32 v20, v20
	s_nop 0
	v_add_f32_e32 v20, 1.0, v20
	v_rcp_f32_e32 v20, v20
	s_nop 0
	v_mul_f32_e32 v99, v20, v26
	v_add_co_u32_e32 v20, vcc, s89, v14
	s_nop 1
	v_addc_co_u32_e32 v21, vcc, 0, v15, vcc
	v_lshlrev_b32_e32 v26, 16, v149
	v_add_co_u32_e32 v20, vcc, s89, v12
	s_nop 1
	v_addc_co_u32_e32 v21, vcc, 0, v13, vcc
	v_mul_f32_e32 v21, 0xbfb8aa3b, v26
	v_exp_f32_e32 v21, v21
	v_lshlrev_b32_e32 v20, 16, v181
	v_add_f32_e32 v21, 1.0, v21
	v_rcp_f32_e32 v21, v21
	v_mul_f32_e32 v20, 0xbfb8aa3b, v20
	v_exp_f32_e32 v20, v20
	v_mul_f32_e32 v95, v21, v26
	v_add_co_u32_e32 v26, vcc, s16, v14
	v_add_f32_e32 v20, 1.0, v20
	s_nop 0
	v_addc_co_u32_e32 v27, vcc, 0, v15, vcc
	v_add_co_u32_e32 v26, vcc, s17, v12
	v_rcp_f32_e32 v20, v20
	s_nop 0
	v_addc_co_u32_e32 v27, vcc, 0, v13, vcc
	v_lshlrev_b32_e32 v28, 16, v150
	v_mul_f32_e32 v26, 0xbfb8aa3b, v28
	v_exp_f32_e32 v26, v26
	v_lshlrev_b32_e32 v21, 16, v182
	v_add_f32_e32 v26, 1.0, v26
	v_rcp_f32_e32 v26, v26
	v_mul_f32_e32 v21, 0xbfb8aa3b, v21
	v_exp_f32_e32 v21, v21
	v_mul_f32_e32 v98, v26, v28
	v_add_co_u32_e32 v26, vcc, s6, v14
	v_add_f32_e32 v21, 1.0, v21
	s_nop 0
	v_addc_co_u32_e32 v27, vcc, 0, v15, vcc
	v_rcp_f32_e32 v21, v21
	v_lshlrev_b32_e32 v29, 16, v151
	v_add_co_u32_e32 v26, vcc, s0, v12
	s_mov_b32 s0, 0x2a000
	s_nop 0
	v_addc_co_u32_e32 v27, vcc, 0, v13, vcc
	v_lshlrev_b32_e32 v26, 16, v183
	v_mul_f32_e32 v26, 0xbfb8aa3b, v26
	v_exp_f32_e32 v26, v26
	s_nop 0
	v_add_f32_e32 v26, 1.0, v26
	v_rcp_f32_e32 v28, v26
	v_mul_f32_e32 v26, 0xbfb8aa3b, v29
	v_exp_f32_e32 v26, v26
	s_nop 0
	v_add_f32_e32 v26, 1.0, v26
	v_rcp_f32_e32 v26, v26
	s_nop 0
	v_mul_f32_e32 v101, v26, v29
	v_add_co_u32_e32 v26, vcc, s0, v14
	s_mov_b32 s0, 0x31000
	s_nop 0
	v_addc_co_u32_e32 v27, vcc, 0, v15, vcc
	v_lshlrev_b32_e32 v30, 16, v152
	v_add_co_u32_e32 v26, vcc, s18, v12
	s_nop 1
	v_addc_co_u32_e32 v27, vcc, 0, v13, vcc
	v_lshlrev_b32_e32 v26, 16, v186
	v_mul_f32_e32 v26, 0xbfb8aa3b, v26
	v_exp_f32_e32 v26, v26
	s_nop 0
	v_add_f32_e32 v26, 1.0, v26
	v_rcp_f32_e32 v29, v26
	v_mul_f32_e32 v26, 0xbfb8aa3b, v30
	v_exp_f32_e32 v26, v26
	s_nop 0
	v_add_f32_e32 v26, 1.0, v26
	v_rcp_f32_e32 v26, v26
	s_nop 0
	v_mul_f32_e32 v103, v26, v30
	v_add_co_u32_e32 v26, vcc, s9, v14
	s_nop 1
	v_addc_co_u32_e32 v27, vcc, 0, v15, vcc
	v_lshlrev_b32_e32 v30, 16, v153
	v_add_co_u32_e32 v26, vcc, s9, v12
	s_nop 1
	v_addc_co_u32_e32 v27, vcc, 0, v13, vcc
	v_mul_f32_e32 v27, 0xbfb8aa3b, v30
	v_exp_f32_e32 v27, v27
	v_lshlrev_b32_e32 v26, 16, v187
	v_add_f32_e32 v27, 1.0, v27
	v_rcp_f32_e32 v27, v27
	v_mul_f32_e32 v26, 0xbfb8aa3b, v26
	v_exp_f32_e32 v26, v26
	v_mul_f32_e32 v102, v27, v30
	v_add_co_u32_e32 v30, vcc, s0, v14
	s_mov_b32 s0, 0x35000
	s_nop 0
	v_addc_co_u32_e32 v31, vcc, 0, v15, vcc
	v_add_co_u32_e32 v30, vcc, s96, v12
	v_add_f32_e32 v26, 1.0, v26
	s_nop 0
	v_addc_co_u32_e32 v31, vcc, 0, v13, vcc
	v_rcp_f32_e32 v26, v26
	v_lshlrev_b32_e32 v32, 16, v154
	v_mul_f32_e32 v30, 0xbfb8aa3b, v32
	v_exp_f32_e32 v30, v30
	v_lshlrev_b32_e32 v27, 16, v188
	v_add_f32_e32 v30, 1.0, v30
	v_rcp_f32_e32 v30, v30
	v_mul_f32_e32 v27, 0xbfb8aa3b, v27
	v_exp_f32_e32 v27, v27
	v_mul_f32_e32 v104, v30, v32
	v_add_co_u32_e32 v30, vcc, s0, v14
	s_mov_b32 s0, 0x34000
	s_nop 0
	v_addc_co_u32_e32 v31, vcc, 0, v15, vcc
	v_add_f32_e32 v27, 1.0, v27
	v_rcp_f32_e32 v27, v27
	v_lshlrev_b32_e32 v32, 16, v155
	v_add_co_u32_e32 v30, vcc, s0, v12
	s_mov_b32 s0, 0x39000
	s_nop 0
	v_addc_co_u32_e32 v31, vcc, 0, v13, vcc
	v_mul_f32_e32 v31, 0xbfb8aa3b, v32
	v_exp_f32_e32 v31, v31
	v_lshlrev_b32_e32 v30, 16, v189
	v_add_f32_e32 v31, 1.0, v31
	v_rcp_f32_e32 v31, v31
	v_mul_f32_e32 v30, 0xbfb8aa3b, v30
	v_exp_f32_e32 v30, v30
	v_mul_f32_e32 v105, v31, v32
	v_add_co_u32_e32 v32, vcc, s0, v14
	s_mov_b32 s0, 0x40000
	s_nop 0
	v_addc_co_u32_e32 v33, vcc, 0, v15, vcc
	v_add_co_u32_e32 v32, vcc, s19, v12
	v_add_f32_e32 v30, 1.0, v30
	s_nop 0
	v_addc_co_u32_e32 v33, vcc, 0, v13, vcc
	v_rcp_f32_e32 v30, v30
	v_lshlrev_b32_e32 v34, 16, v156
	v_mul_f32_e32 v32, 0xbfb8aa3b, v34
	v_exp_f32_e32 v32, v32
	v_lshlrev_b32_e32 v31, 16, v190
	v_add_f32_e32 v32, 1.0, v32
	v_rcp_f32_e32 v32, v32
	v_mul_f32_e32 v31, 0xbfb8aa3b, v31
	v_exp_f32_e32 v31, v31
	v_mul_f32_e32 v106, v32, v34
	v_add_co_u32_e32 v32, vcc, s10, v14
	v_add_f32_e32 v31, 1.0, v31
	s_nop 0
	v_addc_co_u32_e32 v33, vcc, 0, v15, vcc
	v_rcp_f32_e32 v31, v31
	v_lshlrev_b32_e32 v34, 16, v157
	v_add_co_u32_e32 v32, vcc, s10, v12
	s_nop 1
	v_addc_co_u32_e32 v33, vcc, 0, v13, vcc
	v_mul_f32_e32 v33, 0xbfb8aa3b, v34
	v_exp_f32_e32 v33, v33
	v_lshlrev_b32_e32 v32, 16, v191
	v_add_f32_e32 v33, 1.0, v33
	v_rcp_f32_e32 v33, v33
	v_mul_f32_e32 v32, 0xbfb8aa3b, v32
	v_exp_f32_e32 v32, v32
	v_mul_f32_e32 v107, v33, v34
	v_add_co_u32_e32 v34, vcc, s0, v14
	s_mov_b32 s0, 0x44000
	s_nop 0
	v_addc_co_u32_e32 v35, vcc, 0, v15, vcc
	v_add_co_u32_e32 v34, vcc, s20, v12
	v_add_f32_e32 v32, 1.0, v32
	s_nop 0
	v_addc_co_u32_e32 v35, vcc, 0, v13, vcc
	v_rcp_f32_e32 v32, v32
	v_lshlrev_b32_e32 v36, 16, v158
	v_mul_f32_e32 v34, 0xbfb8aa3b, v36
	v_exp_f32_e32 v34, v34
	v_lshlrev_b32_e32 v33, 16, v192
	v_add_f32_e32 v34, 1.0, v34
	v_rcp_f32_e32 v34, v34
	v_mul_f32_e32 v33, 0xbfb8aa3b, v33
	v_exp_f32_e32 v33, v33
	v_mul_f32_e32 v108, v34, v36
; DI float bf2f(unsigned v) { return __uint_as_float(v << 16); }
; DI float flog(float x) { return __builtin_amdgcn_logf(x) * 0.6931471805599453f; }
; DI float sigm(float x) { return frcp(1.f + fexp(-x)); }
; DI float silu(float x) { return x * sigm(x); }
; DI void hgrn_prep_job(const Frame& F, int job, int layer, LAS unsigned char* scr) {
;     ...
;         for (int t = 0; t < 32; ++t) {
;             const float qx = bf2f(qe[t]), fx = bf2f(fe[t]);
;             const float f = lb + (1.f - lb) * sigm(fx);
;             bsum += flog(f); bq[t] = bsum; kv[t] = 1.f - f; qv[t] = silu(qx);
	v_add_co_u32_e32 v34, vcc, s0, v14
	s_mov_b32 s0, 0x43000
	s_nop 0
	v_addc_co_u32_e32 v35, vcc, 0, v15, vcc
	v_add_f32_e32 v33, 1.0, v33
	v_rcp_f32_e32 v33, v33
	v_lshlrev_b32_e32 v37, 16, v159
	v_add_co_u32_e32 v34, vcc, s0, v12
	s_mov_b32 s0, 0x48000
	s_nop 0
	v_addc_co_u32_e32 v35, vcc, 0, v13, vcc
	v_lshlrev_b32_e32 v34, 16, v193
	v_mul_f32_e32 v34, 0xbfb8aa3b, v34
	v_exp_f32_e32 v34, v34
	s_nop 0
	v_add_f32_e32 v34, 1.0, v34
	v_rcp_f32_e32 v36, v34
	v_mul_f32_e32 v34, 0xbfb8aa3b, v37
	v_exp_f32_e32 v34, v34
	s_nop 0
	v_add_f32_e32 v34, 1.0, v34
	v_rcp_f32_e32 v34, v34
	s_nop 0
	v_mul_f32_e32 v109, v34, v37
	v_add_co_u32_e32 v34, vcc, s0, v14
	s_mov_b32 s0, 0x4f000
	s_nop 0
	v_addc_co_u32_e32 v35, vcc, 0, v15, vcc
	v_lshlrev_b32_e32 v38, 16, v160
	v_add_co_u32_e32 v34, vcc, s21, v12
	s_nop 1
	v_addc_co_u32_e32 v35, vcc, 0, v13, vcc
	v_lshlrev_b32_e32 v34, 16, v194
	v_mul_f32_e32 v34, 0xbfb8aa3b, v34
	v_exp_f32_e32 v34, v34
	s_nop 0
	v_add_f32_e32 v34, 1.0, v34
	v_rcp_f32_e32 v37, v34
	v_mul_f32_e32 v34, 0xbfb8aa3b, v38
	v_exp_f32_e32 v34, v34
	s_nop 0
	v_add_f32_e32 v34, 1.0, v34
	v_rcp_f32_e32 v34, v34
	s_nop 0
	v_mul_f32_e32 v110, v34, v38
	v_add_co_u32_e32 v34, vcc, s11, v14
	s_nop 1
	v_addc_co_u32_e32 v35, vcc, 0, v15, vcc
	v_lshlrev_b32_e32 v38, 16, v161
	v_add_co_u32_e32 v34, vcc, s11, v12
	s_nop 1
	v_addc_co_u32_e32 v35, vcc, 0, v13, vcc
	v_mul_f32_e32 v35, 0xbfb8aa3b, v38
	v_exp_f32_e32 v35, v35
	v_lshlrev_b32_e32 v34, 16, v195
	v_add_f32_e32 v35, 1.0, v35
	v_rcp_f32_e32 v35, v35
	v_mul_f32_e32 v34, 0xbfb8aa3b, v34
	v_exp_f32_e32 v34, v34
	v_mul_f32_e32 v111, v35, v38
	v_add_co_u32_e32 v38, vcc, s0, v14
	s_mov_b32 s0, 0x53000
	s_nop 0
	v_addc_co_u32_e32 v39, vcc, 0, v15, vcc
	v_add_co_u32_e32 v38, vcc, s22, v12
	v_add_f32_e32 v34, 1.0, v34
	s_nop 0
	v_addc_co_u32_e32 v39, vcc, 0, v13, vcc
	v_rcp_f32_e32 v34, v34
	v_lshlrev_b32_e32 v40, 16, v162
	v_mul_f32_e32 v38, 0xbfb8aa3b, v40
	v_exp_f32_e32 v38, v38
	v_lshlrev_b32_e32 v35, 16, v196
	v_add_f32_e32 v38, 1.0, v38
	v_rcp_f32_e32 v38, v38
	v_mul_f32_e32 v35, 0xbfb8aa3b, v35
	v_exp_f32_e32 v35, v35
	v_mul_f32_e32 v112, v38, v40
	v_add_co_u32_e32 v38, vcc, s0, v14
	s_mov_b32 s0, 0x52000
	s_nop 0
	v_addc_co_u32_e32 v39, vcc, 0, v15, vcc
	v_add_f32_e32 v35, 1.0, v35
	v_rcp_f32_e32 v35, v35
	v_lshlrev_b32_e32 v41, 16, v163
	v_add_co_u32_e32 v38, vcc, s0, v12
	s_mov_b32 s0, 0x57000
	s_nop 0
	v_addc_co_u32_e32 v39, vcc, 0, v13, vcc
	v_lshlrev_b32_e32 v38, 16, v197
	v_mul_f32_e32 v38, 0xbfb8aa3b, v38
	v_exp_f32_e32 v38, v38
	s_nop 0
	v_add_f32_e32 v38, 1.0, v38
	v_rcp_f32_e32 v40, v38
	v_mul_f32_e32 v38, 0xbfb8aa3b, v41
	v_exp_f32_e32 v38, v38
	s_nop 0
	v_add_f32_e32 v38, 1.0, v38
	v_rcp_f32_e32 v38, v38
	s_nop 0
	v_mul_f32_e32 v113, v38, v41
	v_add_co_u32_e32 v38, vcc, s0, v14
	s_mov_b32 s0, 0x5e000
	s_nop 0
	v_addc_co_u32_e32 v39, vcc, 0, v15, vcc
	v_lshlrev_b32_e32 v42, 16, v164
	v_add_co_u32_e32 v38, vcc, s23, v12
	s_nop 1
	v_addc_co_u32_e32 v39, vcc, 0, v13, vcc
	v_lshlrev_b32_e32 v38, 16, v198
	v_mul_f32_e32 v38, 0xbfb8aa3b, v38
	v_exp_f32_e32 v38, v38
	s_nop 0
	v_add_f32_e32 v38, 1.0, v38
	v_rcp_f32_e32 v41, v38
	v_mul_f32_e32 v38, 0xbfb8aa3b, v42
	v_exp_f32_e32 v38, v38
	s_nop 0
	v_add_f32_e32 v38, 1.0, v38
	v_rcp_f32_e32 v38, v38
	s_nop 0
	v_mul_f32_e32 v114, v38, v42
	v_add_co_u32_e32 v38, vcc, s12, v14
	s_nop 1
	v_addc_co_u32_e32 v39, vcc, 0, v15, vcc
	v_lshlrev_b32_e32 v42, 16, v165
	v_add_co_u32_e32 v38, vcc, s12, v12
	s_nop 1
	v_addc_co_u32_e32 v39, vcc, 0, v13, vcc
	v_mul_f32_e32 v39, 0xbfb8aa3b, v42
	v_exp_f32_e32 v39, v39
	v_lshlrev_b32_e32 v38, 16, v199
	v_add_f32_e32 v39, 1.0, v39
	v_rcp_f32_e32 v39, v39
	v_mul_f32_e32 v38, 0xbfb8aa3b, v38
	v_exp_f32_e32 v38, v38
	v_mul_f32_e32 v115, v39, v42
	v_add_co_u32_e32 v42, vcc, s0, v14
	s_mov_b32 s0, 0x62000
	s_nop 0
	v_addc_co_u32_e32 v43, vcc, 0, v15, vcc
	v_add_co_u32_e32 v42, vcc, s24, v12
	v_add_f32_e32 v38, 1.0, v38
	s_nop 0
	v_addc_co_u32_e32 v43, vcc, 0, v13, vcc
	v_rcp_f32_e32 v38, v38
	v_lshlrev_b32_e32 v44, 16, v166
	v_mul_f32_e32 v42, 0xbfb8aa3b, v44
	v_exp_f32_e32 v42, v42
	v_lshlrev_b32_e32 v39, 16, v200
	v_add_f32_e32 v42, 1.0, v42
	v_rcp_f32_e32 v42, v42
	v_mul_f32_e32 v39, 0xbfb8aa3b, v39
	v_exp_f32_e32 v39, v39
	v_mul_f32_e32 v116, v42, v44
	v_add_co_u32_e32 v42, vcc, s0, v14
	s_mov_b32 s0, 0x61000
	s_nop 0
	v_addc_co_u32_e32 v43, vcc, 0, v15, vcc
	v_add_f32_e32 v39, 1.0, v39
	v_rcp_f32_e32 v39, v39
	v_lshlrev_b32_e32 v45, 16, v167
	v_add_co_u32_e32 v42, vcc, s0, v12
	s_mov_b32 s0, 0x66000
	s_nop 0
	v_addc_co_u32_e32 v43, vcc, 0, v13, vcc
	v_lshlrev_b32_e32 v42, 16, v201
	v_mul_f32_e32 v42, 0xbfb8aa3b, v42
	v_exp_f32_e32 v42, v42
	s_nop 0
	v_add_f32_e32 v42, 1.0, v42
	v_rcp_f32_e32 v44, v42
	v_mul_f32_e32 v42, 0xbfb8aa3b, v45
	v_exp_f32_e32 v42, v42
	s_nop 0
	v_add_f32_e32 v42, 1.0, v42
	v_rcp_f32_e32 v42, v42
	s_nop 0
	v_mul_f32_e32 v118, v42, v45
	v_add_co_u32_e32 v42, vcc, s0, v14
	s_mov_b32 s0, 0x6d000
	s_nop 0
	v_addc_co_u32_e32 v43, vcc, 0, v15, vcc
	v_lshlrev_b32_e32 v46, 16, v168
	v_add_co_u32_e32 v42, vcc, s25, v12
	s_nop 1
	v_addc_co_u32_e32 v43, vcc, 0, v13, vcc
	v_lshlrev_b32_e32 v42, 16, v202
	v_mul_f32_e32 v42, 0xbfb8aa3b, v42
	v_exp_f32_e32 v42, v42
	s_nop 0
	v_add_f32_e32 v42, 1.0, v42
	v_rcp_f32_e32 v45, v42
	v_mul_f32_e32 v42, 0xbfb8aa3b, v46
	v_exp_f32_e32 v42, v42
	s_nop 0
	v_add_f32_e32 v42, 1.0, v42
	v_rcp_f32_e32 v42, v42
	s_nop 0
	v_mul_f32_e32 v121, v42, v46
	v_add_co_u32_e32 v42, vcc, s13, v14
	s_nop 1
	v_addc_co_u32_e32 v43, vcc, 0, v15, vcc
	v_lshlrev_b32_e32 v46, 16, v169
	v_add_co_u32_e32 v42, vcc, s13, v12
	s_nop 1
	v_addc_co_u32_e32 v43, vcc, 0, v13, vcc
	v_mul_f32_e32 v43, 0xbfb8aa3b, v46
	v_exp_f32_e32 v43, v43
	v_lshlrev_b32_e32 v42, 16, v203
	v_add_f32_e32 v43, 1.0, v43
	v_rcp_f32_e32 v43, v43
	v_mul_f32_e32 v42, 0xbfb8aa3b, v42
	v_exp_f32_e32 v42, v42
	v_mul_f32_e32 v122, v43, v46
	v_add_co_u32_e32 v46, vcc, s0, v14
	s_mov_b32 s0, 0x71000
	s_nop 0
	v_addc_co_u32_e32 v47, vcc, 0, v15, vcc
	v_add_co_u32_e32 v46, vcc, s26, v12
	v_add_f32_e32 v42, 1.0, v42
	s_nop 0
	v_addc_co_u32_e32 v47, vcc, 0, v13, vcc
	v_rcp_f32_e32 v42, v42
	v_lshlrev_b32_e32 v78, 16, v170
	v_mul_f32_e32 v46, 0xbfb8aa3b, v78
	v_exp_f32_e32 v46, v46
	v_lshlrev_b32_e32 v43, 16, v204
	v_add_f32_e32 v46, 1.0, v46
	v_rcp_f32_e32 v46, v46
	v_mul_f32_e32 v43, 0xbfb8aa3b, v43
	v_exp_f32_e32 v43, v43
	v_mul_f32_e32 v123, v46, v78
	v_add_co_u32_e32 v46, vcc, s0, v14
	s_mov_b32 s0, 0x70000
	s_nop 0
	v_addc_co_u32_e32 v47, vcc, 0, v15, vcc
	v_add_f32_e32 v43, 1.0, v43
	v_rcp_f32_e32 v43, v43
	v_lshlrev_b32_e32 v78, 16, v171
	v_add_co_u32_e32 v46, vcc, s0, v12
	s_mov_b32 s0, 0x75000
	s_nop 0
	v_addc_co_u32_e32 v47, vcc, 0, v13, vcc
	v_add_co_u32_e32 v14, vcc, s0, v14
	s_nop 0
	v_addc_co_u32_e32 v15, vcc, 0, v15, vcc
	v_add_co_u32_e32 v12, vcc, s27, v12
	s_nop 0
	v_addc_co_u32_e32 v13, vcc, 0, v13, vcc
	v_mul_f32_e32 v47, 0xbfb8aa3b, v78
	v_exp_f32_e32 v47, v47
	s_mov_b32 s0, 0x3f317218
	v_add_f32_e32 v47, 1.0, v47
	v_rcp_f32_e32 v47, v47
	s_waitcnt vmcnt(2)
; #define GAS __attribute__((address_space(1)))
; DI void hgrn_prep_job(const Frame& F, int job, int layer, LAS unsigned char* scr) {
;     ...
;         const int dk = 64 * half + lane;
;         const float lb = ((const GAS float*)lbs)[dk];
;         const GAS bf16* pq = (const GAS bf16*)(P + m0 * NP + PB_Q + h * 128 + dk); const GAS bf16* pf = (const GAS bf16*)(P + m0 * NP + PB_F + h * 128 + dk); const GAS bf16* pv = (const GAS bf16*)(P + m0 * NP + PB_I + h * 128 + dk);
;         unsigned short ve[32];
; #pragma unroll
;         for (int t = 0; t < 32; ++t) ve[t] = pv[(size_t)t * NP];
;         float bq[32], kv[32], qv[32]; float bsum = 0.f;
;         unsigned short qe[32], fe[32];
; #pragma unroll
;         for (int t = 0; t < 32; ++t) { qe[t] = pq[(size_t)t * NP]; fe[t] = pf[(size_t)t * NP]; }
	v_lshlrev_b32_e32 v46, 16, v205
	v_mul_f32_e32 v117, v47, v78
	v_mul_f32_e32 v46, 0xbfb8aa3b, v46
	v_exp_f32_e32 v46, v46
	s_waitcnt vmcnt(1)
	v_lshlrev_b32_e32 v14, 16, v172
	v_add_f32_e32 v46, 1.0, v46
	v_lshlrev_b32_e32 v12, 16, v206
	s_cmp_eq_u64 s[82:83], 0
	s_cbranch_scc1 .Lhg_skip_pf
	v_add_u32_e32 v139, 0x80, v139
	global_load_ushort v141, v139, s[66:67] offset:3072
	global_load_ushort v173, v139, s[68:69]
	v_add_u32_e32 v140, 0x3c00, v139
	global_load_ushort v142, v140, s[66:67] offset:3072
	global_load_ushort v174, v140, s[68:69]
	v_add_u32_e32 v140, 0x7800, v139
	global_load_ushort v143, v140, s[66:67] offset:3072
	global_load_ushort v175, v140, s[68:69]
	v_add_u32_e32 v140, 0xb400, v139
	global_load_ushort v144, v140, s[66:67] offset:3072
	global_load_ushort v176, v140, s[68:69]
	v_add_u32_e32 v140, 0xf000, v139
	global_load_ushort v145, v140, s[66:67] offset:3072
	global_load_ushort v177, v140, s[68:69]
	v_add_u32_e32 v140, 0x12c00, v139
	global_load_ushort v146, v140, s[66:67] offset:3072
	global_load_ushort v178, v140, s[68:69]
	v_add_u32_e32 v140, 0x16800, v139
	global_load_ushort v147, v140, s[66:67] offset:3072
	global_load_ushort v179, v140, s[68:69]
	v_add_u32_e32 v140, 0x1a400, v139
	global_load_ushort v148, v140, s[66:67] offset:3072
	global_load_ushort v180, v140, s[68:69]
	v_add_u32_e32 v140, 0x1e000, v139
	global_load_ushort v149, v140, s[66:67] offset:3072
	global_load_ushort v181, v140, s[68:69]
	v_add_u32_e32 v140, 0x21c00, v139
	global_load_ushort v150, v140, s[66:67] offset:3072
	global_load_ushort v182, v140, s[68:69]
	v_add_u32_e32 v140, 0x25800, v139
	global_load_ushort v151, v140, s[66:67] offset:3072
	global_load_ushort v183, v140, s[68:69]
	v_add_u32_e32 v140, 0x29400, v139
	global_load_ushort v152, v140, s[66:67] offset:3072
	global_load_ushort v186, v140, s[68:69]
	v_add_u32_e32 v140, 0x2d000, v139
	global_load_ushort v153, v140, s[66:67] offset:3072
	global_load_ushort v187, v140, s[68:69]
	v_add_u32_e32 v140, 0x30c00, v139
	global_load_ushort v154, v140, s[66:67] offset:3072
	global_load_ushort v188, v140, s[68:69]
	v_add_u32_e32 v140, 0x34800, v139
	global_load_ushort v155, v140, s[66:67] offset:3072
	global_load_ushort v189, v140, s[68:69]
	v_add_u32_e32 v140, 0x38400, v139
	global_load_ushort v156, v140, s[66:67] offset:3072
	global_load_ushort v190, v140, s[68:69]
	v_add_u32_e32 v140, 0x3c000, v139
	global_load_ushort v157, v140, s[66:67] offset:3072
	global_load_ushort v191, v140, s[68:69]
	v_add_u32_e32 v140, 0x3fc00, v139
	global_load_ushort v158, v140, s[66:67] offset:3072
	global_load_ushort v192, v140, s[68:69]
	v_add_u32_e32 v140, 0x43800, v139
	global_load_ushort v159, v140, s[66:67] offset:3072
	global_load_ushort v193, v140, s[68:69]
	v_add_u32_e32 v140, 0x47400, v139
	global_load_ushort v160, v140, s[66:67] offset:3072
	global_load_ushort v194, v140, s[68:69]
	v_add_u32_e32 v140, 0x4b000, v139
	global_load_ushort v161, v140, s[66:67] offset:3072
	global_load_ushort v195, v140, s[68:69]
	v_add_u32_e32 v140, 0x4ec00, v139
	global_load_ushort v162, v140, s[66:67] offset:3072
	global_load_ushort v196, v140, s[68:69]
	v_add_u32_e32 v140, 0x52800, v139
	global_load_ushort v163, v140, s[66:67] offset:3072
	global_load_ushort v197, v140, s[68:69]
	v_add_u32_e32 v140, 0x56400, v139
	global_load_ushort v164, v140, s[66:67] offset:3072
	global_load_ushort v198, v140, s[68:69]
	v_add_u32_e32 v140, 0x5a000, v139
	global_load_ushort v165, v140, s[66:67] offset:3072
	global_load_ushort v199, v140, s[68:69]
	v_add_u32_e32 v140, 0x5dc00, v139
	global_load_ushort v166, v140, s[66:67] offset:3072
	global_load_ushort v200, v140, s[68:69]
	v_add_u32_e32 v140, 0x61800, v139
	global_load_ushort v167, v140, s[66:67] offset:3072
	global_load_ushort v201, v140, s[68:69]
	v_add_u32_e32 v140, 0x65400, v139
	global_load_ushort v168, v140, s[66:67] offset:3072
	global_load_ushort v202, v140, s[68:69]
	v_add_u32_e32 v140, 0x69000, v139
	global_load_ushort v169, v140, s[66:67] offset:3072
	global_load_ushort v203, v140, s[68:69]
	v_add_u32_e32 v140, 0x6cc00, v139
	global_load_ushort v170, v140, s[66:67] offset:3072
	global_load_ushort v204, v140, s[68:69]
	v_add_u32_e32 v140, 0x70800, v139
	global_load_ushort v171, v140, s[66:67] offset:3072
	global_load_ushort v205, v140, s[68:69]
	v_add_u32_e32 v140, 0x74400, v139
	global_load_ushort v172, v140, s[66:67] offset:3072
	global_load_ushort v206, v140, s[68:69]
	v_lshlrev_b32_e32 v208, 1, v139
	global_load_dword v207, v208, s[56:57]
; #define GAS __attribute__((address_space(1)))
; #define LAS __attribute__((address_space(3)))
; DI unsigned pk2(float lo, float hi) { f32x2 v = {lo, hi}; bf16x2_t b = __builtin_convertvector(v, bf16x2_t); return __builtin_bit_cast(unsigned, b); }
; DI float bf2f(unsigned v) { return __uint_as_float(v << 16); }
; DI float fexp(float x) { return __builtin_amdgcn_exp2f(x * 1.4426950408889634f); }
; DI float flog(float x) { return __builtin_amdgcn_logf(x) * 0.6931471805599453f; }
; DI float frcp(float x) { return __builtin_amdgcn_rcpf(x); }
; DI float sigm(float x) { return frcp(1.f + fexp(-x)); }
; DI float silu(float x) { return x * sigm(x); }
; DI void hgrn_prep_job(const Frame& F, int job, int layer, LAS unsigned char* scr) {
;     ...
;         for (int t = 0; t < 32; ++t) {
;             const float qx = bf2f(qe[t]), fx = bf2f(fe[t]);
;             const float f = lb + (1.f - lb) * sigm(fx);
;             bsum += flog(f); bq[t] = bsum; kv[t] = 1.f - f; qv[t] = silu(qx);
;         }
;         ((GAS float*)he)[dk] = fexp(bsum);
; #pragma unroll
;         for (int t = 0; t < 32; ++t) {
;             const float e = fexp(bq[t]);
;             *(LAS bf16*)(QL + t * 272 + dk * 2) = (bf16)(pk2(qv[t] * e, 0.f) & 0xffffu);
;             *(LAS bf16*)(KL + t * 272 + dk * 2) = (bf16)(pk2(kv[t] * frcp(e), 0.f) & 0xffffu);
;             kv[t] = kv[t] * fexp(bsum - bq[t]);
;         }
.Lhg_skip_pf:
	v_mul_f32_e32 v12, 0xbfb8aa3b, v12
	v_exp_f32_e32 v12, v12
	v_rcp_f32_e32 v46, v46
	v_add_f32_e32 v12, 1.0, v12
	v_rcp_f32_e32 v47, v12
	v_mul_f32_e32 v12, 0xbfb8aa3b, v14
	v_exp_f32_e32 v12, v12
	s_nop 0
	v_add_f32_e32 v12, 1.0, v12
	v_rcp_f32_e32 v12, v12
	s_nop 0
	v_mul_f32_e32 v120, v12, v14
	v_pk_fma_f32 v[14:15], v[6:7], v[16:17], v[4:5] op_sel_hi:[0,1,0]
	v_log_f32_e32 v16, v14
	v_lshl_add_u64 v[12:13], s[64:65], 0, v[10:11]
	v_pk_fma_f32 v[10:11], v[6:7], v[36:37], v[4:5] op_sel_hi:[0,1,0]
	v_log_f32_e32 v124, v10
	v_fma_f32 v128, v16, s0, 0
	v_log_f32_e32 v16, v15
	v_log_f32_e32 v125, v11
	v_pk_add_f32 v[36:37], v[10:11], 1.0 op_sel_hi:[1,0] neg_lo:[1,0] neg_hi:[1,0]
	v_pk_fma_f32 v[10:11], v[6:7], v[32:33], v[4:5] op_sel_hi:[0,1,0]
	v_fmamk_f32 v129, v16, 0x3f317218, v128
	v_mul_f32_e32 v16, 0x3fb8aa3b, v128
	v_exp_f32_e32 v130, v16
	v_add_co_u32_e32 v16, vcc, s14, v8
	v_log_f32_e32 v126, v10
	s_nop 0
	v_addc_co_u32_e32 v17, vcc, 0, v9, vcc
	global_load_ushort v78, v[16:17], off offset:3072
	v_add_co_u32_e32 v16, vcc, s15, v8
	v_log_f32_e32 v127, v11
	s_nop 0
	v_addc_co_u32_e32 v17, vcc, 0, v9, vcc
	global_load_ushort v79, v[16:17], off offset:1024
	v_add_co_u32_e32 v16, vcc, s20, v8
	v_pk_add_f32 v[32:33], v[10:11], 1.0 op_sel_hi:[1,0] neg_lo:[1,0] neg_hi:[1,0]
	s_nop 0
	v_addc_co_u32_e32 v17, vcc, 0, v9, vcc
	v_pk_fma_f32 v[10:11], v[6:7], v[24:25], v[4:5] op_sel_hi:[0,1,0]
	v_mul_f32_e32 v7, v7, v130
	global_load_ushort v80, v[16:17], off offset:3072
	v_add_co_u32_e32 v16, vcc, s21, v8
	v_cvt_pk_bf16_f32 v7, v7, s0
	s_nop 0
	v_addc_co_u32_e32 v17, vcc, 0, v9, vcc
	global_load_ushort v81, v[16:17], off offset:1024
	v_add_co_u32_e32 v16, vcc, s37, v8
	ds_write_b16 v119, v7
	v_rcp_f32_e32 v7, v130
	v_addc_co_u32_e32 v17, vcc, 0, v9, vcc
	global_load_ushort v82, v[16:17], off offset:3072
	v_add_co_u32_e32 v16, vcc, s5, v8
	v_pk_add_f32 v[14:15], v[14:15], 1.0 op_sel_hi:[1,0] neg_lo:[1,0] neg_hi:[1,0]
	s_nop 0
	v_addc_co_u32_e32 v17, vcc, 0, v9, vcc
	global_load_ushort v83, v[16:17], off offset:1024
	v_add_co_u32_e32 v16, vcc, s22, v8
	v_mul_f32_e32 v7, v14, v7
	s_nop 0
	v_addc_co_u32_e32 v17, vcc, 0, v9, vcc
	v_cvt_pk_bf16_f32 v7, v7, s0
	global_load_ushort v84, v[16:17], off offset:3072
	v_add_co_u32_e32 v16, vcc, s23, v8
	ds_write_b16 v119, v7 offset:8704
	v_mul_f32_e32 v7, 0x3fb8aa3b, v129
	v_addc_co_u32_e32 v17, vcc, 0, v9, vcc
	v_exp_f32_e32 v7, v7
	global_load_ushort v85, v[16:17], off offset:1024
	v_add_co_u32_e32 v16, vcc, s17, v8
	v_mul_f32_e32 v5, v5, v7
	s_nop 0
	v_addc_co_u32_e32 v17, vcc, 0, v9, vcc
	global_load_ushort v86, v[16:17], off offset:3072
	v_add_co_u32_e32 v16, vcc, s18, v8
	v_cvt_pk_bf16_f32 v5, v5, s0
	s_nop 0
	v_addc_co_u32_e32 v17, vcc, 0, v9, vcc
	global_load_ushort v87, v[16:17], off offset:1024
	v_add_co_u32_e32 v16, vcc, s24, v8
	ds_write_b16 v119, v5 offset:272
	s_nop 0
	v_addc_co_u32_e32 v17, vcc, 0, v9, vcc
	v_rcp_f32_e32 v5, v7
	v_log_f32_e32 v24, v10
	global_load_ushort v88, v[16:17], off offset:3072
	v_add_co_u32_e32 v16, vcc, s25, v8
	v_mul_f32_e32 v5, v15, v5
	s_nop 0
	v_addc_co_u32_e32 v17, vcc, 0, v9, vcc
	global_load_ushort v89, v[16:17], off offset:1024
	v_add_co_u32_e32 v16, vcc, s96, v8
	v_cvt_pk_bf16_f32 v5, v5, s0
	s_nop 0
	v_addc_co_u32_e32 v17, vcc, 0, v9, vcc
	global_load_ushort v90, v[16:17], off offset:3072
	v_add_co_u32_e32 v16, vcc, s19, v8
	v_fmamk_f32 v7, v24, 0x3f317218, v129
	s_nop 0
	v_addc_co_u32_e32 v17, vcc, 0, v9, vcc
	ds_write_b16 v119, v5 offset:8976
	v_mul_f32_e32 v5, 0x3fb8aa3b, v7
	global_load_ushort v92, v[16:17], off offset:1024
	v_add_co_u32_e32 v16, vcc, s26, v8
	v_exp_f32_e32 v5, v5
	s_nop 0
	v_addc_co_u32_e32 v17, vcc, 0, v9, vcc
	v_add_co_u32_e32 v8, vcc, s27, v8
	global_load_ushort v93, v[16:17], off offset:3072
	s_nop 0
	v_addc_co_u32_e32 v9, vcc, 0, v9, vcc
	global_load_ushort v94, v[8:9], off offset:1024
	v_mul_f32_e32 v8, v74, v5
	v_rcp_f32_e32 v5, v5
	v_log_f32_e32 v25, v11
	v_pk_add_f32 v[10:11], v[10:11], 1.0 op_sel_hi:[1,0] neg_lo:[1,0] neg_hi:[1,0]
	v_cvt_pk_bf16_f32 v8, v8, s0
	v_mul_f32_e32 v5, v10, v5
	v_fmamk_f32 v130, v25, 0x3f317218, v7
	v_cvt_pk_bf16_f32 v5, v5, s0
	ds_write_b16 v119, v5 offset:9248
	v_mul_f32_e32 v5, 0x3fb8aa3b, v130
	v_exp_f32_e32 v5, v5
	ds_write_b16 v119, v8 offset:544
	s_and_b64 vcc, exec, s[82:83]
	s_mov_b64 s[82:83], 0
	v_mul_f32_e32 v8, v76, v5
	v_rcp_f32_e32 v5, v5
	v_cvt_pk_bf16_f32 v8, v8, s0
	ds_write_b16 v119, v8 offset:816
	v_mul_f32_e32 v5, v11, v5
	v_cvt_pk_bf16_f32 v5, v5, s0
	v_pk_fma_f32 v[8:9], v[6:7], v[40:41], v[4:5] op_sel_hi:[0,1,0]
	v_log_f32_e32 v74, v8
	v_log_f32_e32 v76, v9
	v_pk_add_f32 v[40:41], v[8:9], 1.0 op_sel_hi:[1,0] neg_lo:[1,0] neg_hi:[1,0]
	v_pk_fma_f32 v[8:9], v[6:7], v[34:35], v[4:5] op_sel_hi:[0,1,0]
	v_log_f32_e32 v131, v8
	v_log_f32_e32 v132, v9
	v_pk_add_f32 v[24:25], v[8:9], 1.0 op_sel_hi:[1,0] neg_lo:[1,0] neg_hi:[1,0]
	v_pk_fma_f32 v[8:9], v[6:7], v[22:23], v[4:5] op_sel_hi:[0,1,0]
	ds_write_b16 v119, v5 offset:9520
	v_log_f32_e32 v5, v8
	v_log_f32_e32 v22, v9
	v_pk_add_f32 v[16:17], v[8:9], 1.0 op_sel_hi:[1,0] neg_lo:[1,0] neg_hi:[1,0]
	v_pk_fma_f32 v[8:9], v[6:7], v[18:19], v[4:5] op_sel_hi:[0,1,0]
	v_log_f32_e32 v18, v8
	v_log_f32_e32 v19, v9
	v_pk_add_f32 v[8:9], v[8:9], 1.0 op_sel_hi:[1,0] neg_lo:[1,0] neg_hi:[1,0]
	v_fmamk_f32 v133, v18, 0x3f317218, v130
	v_mul_f32_e32 v18, 0x3fb8aa3b, v133
	v_exp_f32_e32 v18, v18
	v_fmamk_f32 v134, v19, 0x3f317218, v133
	v_mul_f32_e32 v19, v75, v18
	v_rcp_f32_e32 v18, v18
	v_cvt_pk_bf16_f32 v19, v19, s0
	ds_write_b16 v119, v19 offset:1088
	v_fmamk_f32 v75, v5, 0x3f317218, v134
	v_mul_f32_e32 v18, v8, v18
; #define GAS __attribute__((address_space(1)))
; #define LAS __attribute__((address_space(3)))
; DI unsigned pk2(float lo, float hi) { f32x2 v = {lo, hi}; bf16x2_t b = __builtin_convertvector(v, bf16x2_t); return __builtin_bit_cast(unsigned, b); }
; DI float fexp(float x) { return __builtin_amdgcn_exp2f(x * 1.4426950408889634f); }
; DI float flog(float x) { return __builtin_amdgcn_logf(x) * 0.6931471805599453f; }
; DI float frcp(float x) { return __builtin_amdgcn_rcpf(x); }
; DI float sigm(float x) { return frcp(1.f + fexp(-x)); }
; DI float silu(float x) { return x * sigm(x); }
; DI void hgrn_prep_job(const Frame& F, int job, int layer, LAS unsigned char* scr) {
;     ...
;             const float f = lb + (1.f - lb) * sigm(fx);
;             bsum += flog(f); bq[t] = bsum; kv[t] = 1.f - f; qv[t] = silu(qx);
;         }
;         ((GAS float*)he)[dk] = fexp(bsum);
; #pragma unroll
;         for (int t = 0; t < 32; ++t) {
;             const float e = fexp(bq[t]);
;             *(LAS bf16*)(QL + t * 272 + dk * 2) = (bf16)(pk2(qv[t] * e, 0.f) & 0xffffu);
;             *(LAS bf16*)(KL + t * 272 + dk * 2) = (bf16)(pk2(kv[t] * frcp(e), 0.f) & 0xffffu);
;             kv[t] = kv[t] * fexp(bsum - bq[t]);
	v_cvt_pk_bf16_f32 v18, v18, s0
	ds_write_b16 v119, v18 offset:9792
	v_mul_f32_e32 v18, 0x3fb8aa3b, v134
	v_exp_f32_e32 v18, v18
	v_mul_f32_e32 v5, 0x3fb8aa3b, v75
	v_exp_f32_e32 v5, v5
	v_mul_f32_e32 v19, v77, v18
	v_rcp_f32_e32 v18, v18
	v_fmamk_f32 v77, v22, 0x3f317218, v75
	v_cvt_pk_bf16_f32 v19, v19, s0
	ds_write_b16 v119, v19 offset:1360
	v_mul_f32_e32 v18, v9, v18
	v_cvt_pk_bf16_f32 v18, v18, s0
	ds_write_b16 v119, v18 offset:10064
	v_mul_f32_e32 v18, v91, v5
	v_rcp_f32_e32 v5, v5
	v_cvt_pk_bf16_f32 v18, v18, s0
	ds_write_b16 v119, v18 offset:1632
	v_mul_f32_e32 v5, v16, v5
	v_cvt_pk_bf16_f32 v5, v5, s0
	ds_write_b16 v119, v5 offset:10336
	v_mul_f32_e32 v5, 0x3fb8aa3b, v77
	v_exp_f32_e32 v5, v5
	s_nop 0
	v_mul_f32_e32 v18, v99, v5
	v_rcp_f32_e32 v5, v5
	v_cvt_pk_bf16_f32 v18, v18, s0
	ds_write_b16 v119, v18 offset:1904
	v_mul_f32_e32 v5, v17, v5
	v_cvt_pk_bf16_f32 v5, v5, s0
	v_pk_fma_f32 v[18:19], v[6:7], v[44:45], v[4:5] op_sel_hi:[0,1,0]
	v_log_f32_e32 v91, v18
	v_log_f32_e32 v99, v19
	v_pk_add_f32 v[34:35], v[18:19], 1.0 op_sel_hi:[1,0] neg_lo:[1,0] neg_hi:[1,0]
	v_pk_fma_f32 v[18:19], v[6:7], v[38:39], v[4:5] op_sel_hi:[0,1,0]
	v_log_f32_e32 v135, v18
	v_log_f32_e32 v136, v19
	v_pk_add_f32 v[38:39], v[18:19], 1.0 op_sel_hi:[1,0] neg_lo:[1,0] neg_hi:[1,0]
	v_pk_fma_f32 v[18:19], v[6:7], v[28:29], v[4:5] op_sel_hi:[0,1,0]
	ds_write_b16 v119, v5 offset:10608
	v_log_f32_e32 v5, v18
	v_log_f32_e32 v22, v19
	v_pk_add_f32 v[18:19], v[18:19], 1.0 op_sel_hi:[1,0] neg_lo:[1,0] neg_hi:[1,0]
	v_pk_fma_f32 v[20:21], v[6:7], v[20:21], v[4:5] op_sel_hi:[0,1,0]
	v_log_f32_e32 v23, v20
	v_log_f32_e32 v28, v21
	v_pk_add_f32 v[20:21], v[20:21], 1.0 op_sel_hi:[1,0] neg_lo:[1,0] neg_hi:[1,0]
	v_fmamk_f32 v29, v23, 0x3f317218, v77
	v_mul_f32_e32 v23, 0x3fb8aa3b, v29
	v_exp_f32_e32 v23, v23
	v_fmamk_f32 v28, v28, 0x3f317218, v29
	v_mul_f32_e32 v44, v95, v23
	v_rcp_f32_e32 v23, v23
	v_fmamk_f32 v95, v5, 0x3f317218, v28
	v_mul_f32_e32 v5, 0x3fb8aa3b, v95
	v_exp_f32_e32 v5, v5
	v_mul_f32_e32 v23, v20, v23
	v_cvt_pk_bf16_f32 v23, v23, s0
	ds_write_b16 v119, v23 offset:10880
	v_mul_f32_e32 v23, 0x3fb8aa3b, v28
	v_exp_f32_e32 v23, v23
	v_cvt_pk_bf16_f32 v44, v44, s0
	ds_write_b16 v119, v44 offset:2176
	v_mul_f32_e32 v44, v98, v23
	v_fmamk_f32 v98, v22, 0x3f317218, v95
	v_mul_f32_e32 v22, v101, v5
	v_rcp_f32_e32 v5, v5
	v_cvt_pk_bf16_f32 v22, v22, s0
	v_rcp_f32_e32 v23, v23
	ds_write_b16 v119, v22 offset:2720
	v_mul_f32_e32 v5, v18, v5
	v_cvt_pk_bf16_f32 v5, v5, s0
	ds_write_b16 v119, v5 offset:11424
	v_mul_f32_e32 v5, 0x3fb8aa3b, v98
	v_exp_f32_e32 v5, v5
	v_mul_f32_e32 v23, v21, v23
	v_cvt_pk_bf16_f32 v23, v23, s0
	v_cvt_pk_bf16_f32 v44, v44, s0
	v_mul_f32_e32 v22, v103, v5
	v_rcp_f32_e32 v5, v5
	v_cvt_pk_bf16_f32 v22, v22, s0
	ds_write_b16 v119, v23 offset:11152
	ds_write_b16 v119, v22 offset:2992
	v_mul_f32_e32 v5, v19, v5
	v_cvt_pk_bf16_f32 v5, v5, s0
	v_pk_fma_f32 v[22:23], v[6:7], v[46:47], v[4:5] op_sel_hi:[0,1,0]
	ds_write_b16 v119, v44 offset:2448
	v_log_f32_e32 v46, v22
	v_log_f32_e32 v47, v23
	v_pk_add_f32 v[44:45], v[22:23], 1.0 op_sel_hi:[1,0] neg_lo:[1,0] neg_hi:[1,0]
	v_pk_fma_f32 v[22:23], v[6:7], v[42:43], v[4:5] op_sel_hi:[0,1,0]
	ds_write_b16 v119, v5 offset:11696
	v_log_f32_e32 v101, v22
	v_log_f32_e32 v103, v23
	v_pk_add_f32 v[42:43], v[22:23], 1.0 op_sel_hi:[1,0] neg_lo:[1,0] neg_hi:[1,0]
	v_pk_fma_f32 v[22:23], v[6:7], v[30:31], v[4:5] op_sel_hi:[0,1,0]
	v_pk_fma_f32 v[4:5], v[6:7], v[26:27], v[4:5] op_sel_hi:[0,1,0]
	v_log_f32_e32 v6, v4
	v_pk_add_f32 v[26:27], v[4:5], 1.0 op_sel_hi:[1,0] neg_lo:[1,0] neg_hi:[1,0]
	v_log_f32_e32 v137, v5
	v_log_f32_e32 v30, v22
	v_fmamk_f32 v138, v6, 0x3f317218, v98
	v_mul_f32_e32 v4, 0x3fb8aa3b, v138
	v_exp_f32_e32 v4, v4
	v_fmamk_f32 v137, v137, 0x3f317218, v138
	v_fmamk_f32 v30, v30, 0x3f317218, v137
	v_log_f32_e32 v31, v23
	v_mul_f32_e32 v5, v102, v4
	v_rcp_f32_e32 v4, v4
	v_cvt_pk_bf16_f32 v5, v5, s0
	ds_write_b16 v119, v5 offset:3264
	v_pk_add_f32 v[22:23], v[22:23], 1.0 op_sel_hi:[1,0] neg_lo:[1,0] neg_hi:[1,0]
	v_mul_f32_e32 v4, v26, v4
	v_cvt_pk_bf16_f32 v4, v4, s0
	ds_write_b16 v119, v4 offset:11968
	v_mul_f32_e32 v4, 0x3fb8aa3b, v137
	v_exp_f32_e32 v4, v4
	v_fmamk_f32 v31, v31, 0x3f317218, v30
	v_fmamk_f32 v102, v126, 0x3f317218, v31
	v_mul_f32_e32 v5, v104, v4
	v_rcp_f32_e32 v4, v4
	v_cvt_pk_bf16_f32 v5, v5, s0
	ds_write_b16 v119, v5 offset:3536
	v_fmamk_f32 v104, v127, 0x3f317218, v102
	v_mul_f32_e32 v4, v27, v4
	v_cvt_pk_bf16_f32 v4, v4, s0
	ds_write_b16 v119, v4 offset:12240
	v_mul_f32_e32 v4, 0x3fb8aa3b, v30
	v_exp_f32_e32 v4, v4
	s_nop 0
	v_mul_f32_e32 v5, v105, v4
	v_rcp_f32_e32 v4, v4
	v_cvt_pk_bf16_f32 v5, v5, s0
	ds_write_b16 v119, v5 offset:3808
	v_fmamk_f32 v105, v124, 0x3f317218, v104
	v_mul_f32_e32 v4, v22, v4
	v_cvt_pk_bf16_f32 v4, v4, s0
	ds_write_b16 v119, v4 offset:12512
	v_mul_f32_e32 v4, 0x3fb8aa3b, v31
	v_exp_f32_e32 v4, v4
	s_nop 0
	v_mul_f32_e32 v5, v106, v4
	v_rcp_f32_e32 v4, v4
	v_cvt_pk_bf16_f32 v5, v5, s0
	ds_write_b16 v119, v5 offset:4080
	v_fmamk_f32 v106, v125, 0x3f317218, v105
	v_mul_f32_e32 v4, v23, v4
	v_cvt_pk_bf16_f32 v4, v4, s0
	ds_write_b16 v119, v4 offset:12784
	v_mul_f32_e32 v4, 0x3fb8aa3b, v102
	v_exp_f32_e32 v4, v4
	s_nop 0
	v_mul_f32_e32 v5, v107, v4
	v_rcp_f32_e32 v4, v4
	v_cvt_pk_bf16_f32 v5, v5, s0
	ds_write_b16 v119, v5 offset:4352
	v_fmamk_f32 v107, v131, 0x3f317218, v106
	v_mul_f32_e32 v4, v32, v4
	v_cvt_pk_bf16_f32 v4, v4, s0
	ds_write_b16 v119, v4 offset:13056
	v_mul_f32_e32 v4, 0x3fb8aa3b, v104
	v_exp_f32_e32 v4, v4
	s_nop 0
	v_mul_f32_e32 v5, v108, v4
	v_rcp_f32_e32 v4, v4
	v_cvt_pk_bf16_f32 v5, v5, s0
	ds_write_b16 v119, v5 offset:4624
; #define GAS __attribute__((address_space(1)))
; #define LAS __attribute__((address_space(3)))
; DI unsigned pk2(float lo, float hi) { f32x2 v = {lo, hi}; bf16x2_t b = __builtin_convertvector(v, bf16x2_t); return __builtin_bit_cast(unsigned, b); }
; DI float fexp(float x) { return __builtin_amdgcn_exp2f(x * 1.4426950408889634f); }
; DI float frcp(float x) { return __builtin_amdgcn_rcpf(x); }
; DI void hgrn_prep_job(const Frame& F, int job, int layer, LAS unsigned char* scr) {
;     ...
;         ((GAS float*)he)[dk] = fexp(bsum);
; #pragma unroll
;         for (int t = 0; t < 32; ++t) {
;             const float e = fexp(bq[t]);
;             *(LAS bf16*)(QL + t * 272 + dk * 2) = (bf16)(pk2(qv[t] * e, 0.f) & 0xffffu);
;             *(LAS bf16*)(KL + t * 272 + dk * 2) = (bf16)(pk2(kv[t] * frcp(e), 0.f) & 0xffffu);
;             kv[t] = kv[t] * fexp(bsum - bq[t]);
;         }
	v_fmamk_f32 v108, v132, 0x3f317218, v107
	v_mul_f32_e32 v4, v33, v4
	v_cvt_pk_bf16_f32 v4, v4, s0
	ds_write_b16 v119, v4 offset:13328
	v_mul_f32_e32 v4, 0x3fb8aa3b, v105
	v_exp_f32_e32 v4, v4
	v_fmamk_f32 v74, v74, 0x3f317218, v108
	v_fmamk_f32 v76, v76, 0x3f317218, v74
	v_mul_f32_e32 v5, v109, v4
	v_rcp_f32_e32 v4, v4
	v_cvt_pk_bf16_f32 v5, v5, s0
	ds_write_b16 v119, v5 offset:4896
	v_fmamk_f32 v109, v135, 0x3f317218, v76
	v_mul_f32_e32 v4, v36, v4
	v_cvt_pk_bf16_f32 v4, v4, s0
	ds_write_b16 v119, v4 offset:13600
	v_mul_f32_e32 v4, 0x3fb8aa3b, v106
	v_exp_f32_e32 v4, v4
	s_nop 0
	v_mul_f32_e32 v5, v110, v4
	v_rcp_f32_e32 v4, v4
	v_cvt_pk_bf16_f32 v5, v5, s0
	ds_write_b16 v119, v5 offset:5168
	v_fmamk_f32 v110, v136, 0x3f317218, v109
	v_mul_f32_e32 v4, v37, v4
	v_cvt_pk_bf16_f32 v4, v4, s0
	ds_write_b16 v119, v4 offset:13872
	v_mul_f32_e32 v4, 0x3fb8aa3b, v107
	v_exp_f32_e32 v4, v4
	v_fmamk_f32 v91, v91, 0x3f317218, v110
	v_fmamk_f32 v99, v99, 0x3f317218, v91
	v_fmamk_f32 v101, v101, 0x3f317218, v99
	v_mul_f32_e32 v5, v111, v4
	v_rcp_f32_e32 v4, v4
	v_cvt_pk_bf16_f32 v5, v5, s0
	ds_write_b16 v119, v5 offset:5440
	v_fmamk_f32 v103, v103, 0x3f317218, v101
	v_mul_f32_e32 v4, v24, v4
	v_cvt_pk_bf16_f32 v4, v4, s0
	ds_write_b16 v119, v4 offset:14144
	v_mul_f32_e32 v4, 0x3fb8aa3b, v108
	v_exp_f32_e32 v4, v4
	v_fmamk_f32 v46, v46, 0x3f317218, v103
	v_fmamk_f32 v47, v47, 0x3f317218, v46
	v_sub_f32_e32 v6, v47, v7
	v_mul_f32_e32 v5, v112, v4
	v_rcp_f32_e32 v4, v4
	v_cvt_pk_bf16_f32 v5, v5, s0
	ds_write_b16 v119, v5 offset:5712
	v_sub_f32_e32 v7, v47, v130
	v_mul_f32_e32 v4, v25, v4
	v_cvt_pk_bf16_f32 v4, v4, s0
	ds_write_b16 v119, v4 offset:14416
	v_mul_f32_e32 v4, 0x3fb8aa3b, v74
	v_exp_f32_e32 v4, v4
	v_mul_f32_e32 v6, 0x3fb8aa3b, v6
	v_mul_f32_e32 v7, 0x3fb8aa3b, v7
	v_exp_f32_e32 v6, v6
	v_mul_f32_e32 v5, v113, v4
	v_rcp_f32_e32 v4, v4
	v_cvt_pk_bf16_f32 v5, v5, s0
	ds_write_b16 v119, v5 offset:5984
	v_exp_f32_e32 v7, v7
	v_mul_f32_e32 v4, v40, v4
	v_cvt_pk_bf16_f32 v4, v4, s0
	ds_write_b16 v119, v4 offset:14688
	v_mul_f32_e32 v4, 0x3fb8aa3b, v76
	v_exp_f32_e32 v4, v4
	v_pk_mul_f32 v[6:7], v[10:11], v[6:7]
	v_sub_f32_e32 v10, v47, v133
	v_sub_f32_e32 v11, v47, v134
	v_mul_f32_e32 v5, v114, v4
	v_rcp_f32_e32 v4, v4
	v_cvt_pk_bf16_f32 v5, v5, s0
	ds_write_b16 v119, v5 offset:6256
	v_mul_f32_e32 v10, 0x3fb8aa3b, v10
	v_mul_f32_e32 v4, v41, v4
	v_cvt_pk_bf16_f32 v4, v4, s0
	ds_write_b16 v119, v4 offset:14960
	v_mul_f32_e32 v4, 0x3fb8aa3b, v109
	v_exp_f32_e32 v4, v4
	v_mul_f32_e32 v11, 0x3fb8aa3b, v11
	v_exp_f32_e32 v10, v10
	v_exp_f32_e32 v11, v11
	v_mul_f32_e32 v5, v115, v4
	v_rcp_f32_e32 v4, v4
	v_cvt_pk_bf16_f32 v5, v5, s0
	ds_write_b16 v119, v5 offset:6528
	v_pk_mul_f32 v[8:9], v[8:9], v[10:11]
	v_mul_f32_e32 v4, v38, v4
	v_cvt_pk_bf16_f32 v4, v4, s0
	ds_write_b16 v119, v4 offset:15232
	v_mul_f32_e32 v4, 0x3fb8aa3b, v110
	v_exp_f32_e32 v4, v4
	v_sub_f32_e32 v10, v47, v75
	v_sub_f32_e32 v11, v47, v77
	v_mul_f32_e32 v10, 0x3fb8aa3b, v10
	v_mul_f32_e32 v5, v116, v4
	v_rcp_f32_e32 v4, v4
	v_cvt_pk_bf16_f32 v5, v5, s0
	ds_write_b16 v119, v5 offset:6800
	v_mul_f32_e32 v11, 0x3fb8aa3b, v11
	v_mul_f32_e32 v4, v39, v4
	v_cvt_pk_bf16_f32 v4, v4, s0
	ds_write_b16 v119, v4 offset:15504
	v_mul_f32_e32 v4, 0x3fb8aa3b, v91
	v_exp_f32_e32 v4, v4
	v_exp_f32_e32 v10, v10
	v_exp_f32_e32 v11, v11
	v_mul_f32_e32 v5, v118, v4
	v_rcp_f32_e32 v4, v4
	v_cvt_pk_bf16_f32 v5, v5, s0
	ds_write_b16 v119, v5 offset:7072
	v_pk_mul_f32 v[10:11], v[16:17], v[10:11]
	v_mul_f32_e32 v4, v34, v4
	v_cvt_pk_bf16_f32 v4, v4, s0
	ds_write_b16 v119, v4 offset:15776
	v_mul_f32_e32 v4, 0x3fb8aa3b, v99
	v_exp_f32_e32 v4, v4
	v_sub_f32_e32 v16, v47, v138
	v_sub_f32_e32 v17, v47, v137
	v_mul_f32_e32 v16, 0x3fb8aa3b, v16
	v_mul_f32_e32 v5, v121, v4
	v_rcp_f32_e32 v4, v4
	v_cvt_pk_bf16_f32 v5, v5, s0
	ds_write_b16 v119, v5 offset:7344
	v_mul_f32_e32 v17, 0x3fb8aa3b, v17
	v_mul_f32_e32 v4, v35, v4
	v_cvt_pk_bf16_f32 v4, v4, s0
	ds_write_b16 v119, v4 offset:16048
	v_mul_f32_e32 v4, 0x3fb8aa3b, v101
	v_exp_f32_e32 v4, v4
	v_exp_f32_e32 v16, v16
	v_exp_f32_e32 v17, v17
	v_mul_f32_e32 v5, v122, v4
	v_rcp_f32_e32 v4, v4
	v_cvt_pk_bf16_f32 v5, v5, s0
	ds_write_b16 v119, v5 offset:7616
	v_pk_mul_f32 v[16:17], v[26:27], v[16:17]
	v_mul_f32_e32 v4, v42, v4
	v_cvt_pk_bf16_f32 v4, v4, s0
	ds_write_b16 v119, v4 offset:16320
	v_mul_f32_e32 v4, 0x3fb8aa3b, v103
	v_exp_f32_e32 v4, v4
	v_sub_f32_e32 v26, v47, v107
	v_sub_f32_e32 v27, v47, v108
	v_mul_f32_e32 v26, 0x3fb8aa3b, v26
	v_mul_f32_e32 v5, v123, v4
	v_rcp_f32_e32 v4, v4
	v_cvt_pk_bf16_f32 v5, v5, s0
	ds_write_b16 v119, v5 offset:7888
	v_sub_f32_e32 v5, v47, v129
	v_mul_f32_e32 v4, v43, v4
	v_cvt_pk_bf16_f32 v4, v4, s0
	ds_write_b16 v119, v4 offset:16592
	v_mul_f32_e32 v4, 0x3fb8aa3b, v47
	v_exp_f32_e32 v111, v4
	v_sub_f32_e32 v4, v47, v128
	v_mul_f32_e32 v4, 0x3fb8aa3b, v4
	v_mul_f32_e32 v5, 0x3fb8aa3b, v5
	v_exp_f32_e32 v4, v4
	v_exp_f32_e32 v5, v5
	global_store_dword v[12:13], v111, off
	v_sub_f32_e32 v12, v47, v29
	v_sub_f32_e32 v13, v47, v28
	v_pk_mul_f32 v[4:5], v[14:15], v[4:5]
	v_sub_f32_e32 v14, v47, v95
	v_sub_f32_e32 v15, v47, v98
	v_mul_f32_e32 v14, 0x3fb8aa3b, v14
	v_mul_f32_e32 v15, 0x3fb8aa3b, v15
	v_exp_f32_e32 v14, v14
	v_exp_f32_e32 v15, v15
	v_mul_f32_e32 v12, 0x3fb8aa3b, v12
	v_mul_f32_e32 v13, 0x3fb8aa3b, v13
	v_exp_f32_e32 v12, v12
	v_pk_mul_f32 v[14:15], v[18:19], v[14:15]
	v_sub_f32_e32 v18, v47, v30
	v_sub_f32_e32 v19, v47, v31
	v_sub_f32_e32 v30, v47, v91
	v_sub_f32_e32 v31, v47, v99
	v_mul_f32_e32 v30, 0x3fb8aa3b, v30
	v_mul_f32_e32 v31, 0x3fb8aa3b, v31
	v_exp_f32_e32 v30, v30
	v_exp_f32_e32 v31, v31
	v_exp_f32_e32 v13, v13
; #define GAS __attribute__((address_space(1)))
; #define LAS __attribute__((address_space(3)))
; #define LDS_WAIT() asm volatile("s_waitcnt lgkmcnt(0)" ::: "memory")
; DI unsigned pk2(float lo, float hi) { f32x2 v = {lo, hi}; bf16x2_t b = __builtin_convertvector(v, bf16x2_t); return __builtin_bit_cast(unsigned, b); }
; DI void hgrn_prep_job(const Frame& F, int job, int layer, LAS unsigned char* scr) {
;     ...
;         for (int g = 0; g < 4; ++g) {
;             v4u w; w.x = pk2(kv[permk(g, 0)], kv[permk(g, 1)]); w.y = pk2(kv[permk(g, 2)], kv[permk(g, 3)]); w.z = pk2(kv[permk(g, 4)], kv[permk(g, 5)]); w.w = pk2(kv[permk(g, 6)], kv[permk(g, 7)]);
;             *(GAS v4u*)(hk + (((dk >> 4) * 64) + (dk & 15) + 16 * g) * 16) = w;
;         }
; #pragma unroll
;         for (int g = 0; g < 4; ++g) {
;             v4u w; w.x = ve[permk(g, 0)] | ((unsigned)ve[permk(g, 1)] << 16); w.y = ve[permk(g, 2)] | ((unsigned)ve[permk(g, 3)] << 16);
;             w.z = ve[permk(g, 4)] | ((unsigned)ve[permk(g, 5)] << 16); w.w = ve[permk(g, 6)] | ((unsigned)ve[permk(g, 7)] << 16);
;             *(GAS v4u*)(hv + (((dk >> 4) * 64) + (dk & 15) + 16 * g) * 16) = w;
;         }
;     }
;     LDS_WAIT(); asm volatile("" ::: "memory");
;     const int r = lane & 15, g = lane >> 4;
; #pragma unroll
;     for (int mt = 0; mt < 2; ++mt)
; #pragma unroll
;         for (int kb = 0; kb < 4; ++kb) {
;             const LAS unsigned char* p = QL + (16 * mt + r) * 272 + (32 * kb + 4 * g) * 2;
;             const v2u lo = *(const LAS v2u*)p, hi = *(const LAS v2u*)(p + 32);
;             *(GAS v4u*)(hq + ((mt * 4 + kb) * 64 + lane) * 16) = (v4u){lo.x, lo.y, hi.x, hi.y};
;         }
;     f32x4 acc[2][2];
; #pragma unroll
;     for (int mt = 0; mt < 2; ++mt)
; #pragma unroll
;         for (int nt = 0; nt < 2; ++nt) acc[mt][nt] = (f32x4){0.f, 0.f, 0.f, 0.f};
; #pragma unroll
;     for (int ks = 0; ks < 4; ++ks) {
;         bf16x8 af[2], bfr[2];
; #pragma unroll
;         for (int mt = 0; mt < 2; ++mt) { af[mt] = *(const LAS bf16x8*)(QL + (16 * mt + r) * 272 + (32 * ks + 8 * g) * 2); bfr[mt] = *(const LAS bf16x8*)(KL + (16 * mt + r) * 272 + (32 * ks + 8 * g) * 2); }
	v_mul_f32_e32 v18, 0x3fb8aa3b, v18
	v_mul_f32_e32 v19, 0x3fb8aa3b, v19
	v_pk_mul_f32 v[30:31], v[34:35], v[30:31]
	v_mul_f32_e32 v34, 0x3fb8aa3b, v46
	v_exp_f32_e32 v34, v34
	v_exp_f32_e32 v18, v18
	v_exp_f32_e32 v19, v19
	v_mul_f32_e32 v27, 0x3fb8aa3b, v27
	v_mul_f32_e32 v35, v117, v34
	v_cvt_pk_bf16_f32 v35, v35, s0
	ds_write_b16 v119, v35 offset:8160
	v_mul_f32_e32 v35, v120, v111
	v_cvt_pk_bf16_f32 v35, v35, s0
	v_pk_mul_f32 v[12:13], v[20:21], v[12:13]
	v_sub_f32_e32 v20, v47, v102
	v_sub_f32_e32 v21, v47, v104
	v_exp_f32_e32 v26, v26
	v_exp_f32_e32 v27, v27
	v_rcp_f32_e32 v34, v34
	ds_write_b16 v119, v35 offset:8432
	v_rcp_f32_e32 v35, v111
	v_mul_f32_e32 v20, 0x3fb8aa3b, v20
	v_mul_f32_e32 v21, 0x3fb8aa3b, v21
	v_pk_mul_f32 v[18:19], v[22:23], v[18:19]
	v_exp_f32_e32 v20, v20
	v_exp_f32_e32 v21, v21
	v_sub_f32_e32 v22, v47, v105
	v_sub_f32_e32 v23, v47, v106
	v_mul_f32_e32 v22, 0x3fb8aa3b, v22
	v_mul_f32_e32 v23, 0x3fb8aa3b, v23
	v_exp_f32_e32 v22, v22
	v_exp_f32_e32 v23, v23
	v_pk_mul_f32 v[24:25], v[24:25], v[26:27]
	v_sub_f32_e32 v26, v47, v74
	v_sub_f32_e32 v27, v47, v76
	v_mul_f32_e32 v34, v44, v34
	v_mul_f32_e32 v35, v45, v35
	v_mul_f32_e32 v26, 0x3fb8aa3b, v26
	v_mul_f32_e32 v27, 0x3fb8aa3b, v27
	v_sub_f32_e32 v28, v47, v109
	v_sub_f32_e32 v29, v47, v110
	v_cvt_pk_bf16_f32 v34, v34, s0
	v_cvt_pk_bf16_f32 v35, v35, s0
	v_pk_mul_f32 v[20:21], v[32:33], v[20:21]
	v_exp_f32_e32 v26, v26
	v_exp_f32_e32 v27, v27
	v_mul_f32_e32 v28, 0x3fb8aa3b, v28
	v_mul_f32_e32 v29, 0x3fb8aa3b, v29
	v_sub_f32_e32 v32, v47, v101
	v_sub_f32_e32 v33, v47, v103
	ds_write_b16 v119, v34 offset:16864
	v_sub_f32_e32 v34, v47, v46
	ds_write_b16 v119, v35 offset:17136
	v_sub_f32_e32 v35, v47, v47
	v_exp_f32_e32 v28, v28
	v_exp_f32_e32 v29, v29
	v_mul_f32_e32 v32, 0x3fb8aa3b, v32
	v_mul_f32_e32 v33, 0x3fb8aa3b, v33
	v_mul_f32_e32 v34, 0x3fb8aa3b, v34
	v_mul_f32_e32 v35, 0x3fb8aa3b, v35
	v_pk_mul_f32 v[22:23], v[36:37], v[22:23]
	v_exp_f32_e32 v32, v32
	v_exp_f32_e32 v33, v33
	v_exp_f32_e32 v34, v34
	v_exp_f32_e32 v35, v35
	v_lshlrev_b32_e32 v36, 2, v96
	s_movk_i32 s0, 0x1c0
	v_and_or_b32 v36, v36, s0, v49
	v_pk_mul_f32 v[26:27], v[40:41], v[26:27]
	v_lshlrev_b32_e32 v36, 4, v36
	v_cvt_pk_bf16_f32 v4, v4, v5
	v_cvt_pk_bf16_f32 v5, v6, v7
	v_cvt_pk_bf16_f32 v6, v20, v21
	v_cvt_pk_bf16_f32 v7, v22, v23
	v_pk_mul_f32 v[28:29], v[38:39], v[28:29]
	global_store_dwordx4 v36, v[4:7], s[60:61]
	v_pk_mul_f32 v[32:33], v[42:43], v[32:33]
	v_pk_mul_f32 v[34:35], v[44:45], v[34:35]
	v_cvt_pk_bf16_f32 v4, v8, v9
	v_cvt_pk_bf16_f32 v5, v10, v11
	v_cvt_pk_bf16_f32 v6, v24, v25
	v_cvt_pk_bf16_f32 v7, v26, v27
	global_store_dwordx4 v36, v[4:7], s[60:61] offset:256
	s_mov_b32 s0, 64
	s_nop 0
	v_cvt_pk_bf16_f32 v4, v12, v13
	v_cvt_pk_bf16_f32 v5, v14, v15
	v_cvt_pk_bf16_f32 v6, v28, v29
	v_cvt_pk_bf16_f32 v7, v30, v31
	global_store_dwordx4 v36, v[4:7], s[60:61] offset:512
	s_nop 1
	v_cvt_pk_bf16_f32 v4, v16, v17
	v_cvt_pk_bf16_f32 v5, v18, v19
	v_cvt_pk_bf16_f32 v6, v32, v33
	v_cvt_pk_bf16_f32 v7, v34, v35
	global_store_dwordx4 v36, v[4:7], s[60:61] offset:768
	s_waitcnt vmcnt(20)
	s_nop 0
	v_lshl_or_b32 v4, v78, 16, v58
	s_waitcnt vmcnt(19)
	v_lshl_or_b32 v5, v79, 16, v59
	s_waitcnt vmcnt(18)
	v_lshl_or_b32 v6, v80, 16, v66
	s_waitcnt vmcnt(17)
	v_lshl_or_b32 v7, v81, 16, v67
	global_store_dwordx4 v36, v[4:7], s[62:63]
	s_waitcnt vmcnt(17)
	s_nop 0
	v_lshl_or_b32 v4, v82, 16, v60
	s_waitcnt vmcnt(16)
	v_lshl_or_b32 v5, v83, 16, v61
	s_waitcnt vmcnt(15)
	v_lshl_or_b32 v6, v84, 16, v68
	s_waitcnt vmcnt(14)
	v_lshl_or_b32 v7, v85, 16, v69
	global_store_dwordx4 v36, v[4:7], s[62:63] offset:256
	s_waitcnt vmcnt(14)
	s_nop 0
	v_lshl_or_b32 v4, v86, 16, v62
	s_waitcnt vmcnt(13)
	v_lshl_or_b32 v5, v87, 16, v63
	s_waitcnt vmcnt(12)
	v_lshl_or_b32 v6, v88, 16, v70
	s_waitcnt vmcnt(11)
	v_lshl_or_b32 v7, v89, 16, v71
	global_store_dwordx4 v36, v[4:7], s[62:63] offset:512
	s_waitcnt vmcnt(11)
	s_nop 0
	v_lshl_or_b32 v4, v90, 16, v64
	s_waitcnt vmcnt(10)
	v_lshl_or_b32 v5, v92, 16, v65
	s_waitcnt vmcnt(9)
	v_lshl_or_b32 v6, v93, 16, v72
	s_waitcnt vmcnt(8)
	v_lshl_or_b32 v7, v94, 16, v73
	global_store_dwordx4 v36, v[4:7], s[62:63] offset:768
	s_cbranch_vccnz .LBB0_810
	s_waitcnt lgkmcnt(0)
	v_add_u32_e32 v10, v50, v51
	ds_read2_b64 v[4:7], v10 offset1:4
	v_lshl_add_u64 v[8:9], v[0:1], 0, s[58:59]
	s_movk_i32 s0, 0x1000
	s_waitcnt lgkmcnt(0)
	global_store_dwordx4 v[8:9], v[4:7], off
	ds_read2_b64 v[4:7], v10 offset0:8 offset1:12
	s_waitcnt lgkmcnt(0)
	global_store_dwordx4 v[8:9], v[4:7], off offset:1024
	ds_read2_b64 v[4:7], v10 offset0:16 offset1:20
	s_waitcnt lgkmcnt(0)
	global_store_dwordx4 v[8:9], v[4:7], off offset:2048
	ds_read2_b64 v[4:7], v10 offset0:24 offset1:28
	v_add_u32_e32 v10, 0x1000, v10
	s_waitcnt lgkmcnt(0)
	global_store_dwordx4 v[8:9], v[4:7], off offset:3072
	ds_read2_b64 v[4:7], v10 offset0:32 offset1:36
	v_add_co_u32_e32 v8, vcc, s0, v8
	s_nop 1
	v_addc_co_u32_e32 v9, vcc, 0, v9, vcc
	s_waitcnt lgkmcnt(0)
	global_store_dwordx4 v[8:9], v[4:7], off
	ds_read2_b64 v[4:7], v10 offset0:40 offset1:44
	s_waitcnt lgkmcnt(0)
	global_store_dwordx4 v[8:9], v[4:7], off offset:1024
	ds_read2_b64 v[4:7], v10 offset0:48 offset1:52
	s_waitcnt lgkmcnt(0)
	global_store_dwordx4 v[8:9], v[4:7], off offset:2048
	ds_read2_b64 v[4:7], v10 offset0:56 offset1:60
	s_waitcnt lgkmcnt(0)
	global_store_dwordx4 v[8:9], v[4:7], off offset:3072
	ds_read_b128 v[4:7], v56
	ds_read_b128 v[8:11], v56 offset:8704
	ds_read_b128 v[12:15], v56 offset:4352
	ds_read_b128 v[16:19], v56 offset:13056
	s_waitcnt lgkmcnt(2)
	v_mfma_f32_16x16x32_bf16 v[4:7], v[4:7], v[8:11], 0
	s_waitcnt lgkmcnt(1)
; #define GAS __attribute__((address_space(1)))
; #define LAS __attribute__((address_space(3)))
; #define LDS_WAIT() asm volatile("s_waitcnt lgkmcnt(0)" ::: "memory")
; DI unsigned pk2(float lo, float hi) { f32x2 v = {lo, hi}; bf16x2_t b = __builtin_convertvector(v, bf16x2_t); return __builtin_bit_cast(unsigned, b); }
; DI void hgrn_prep_job(const Frame& F, int job, int layer, LAS unsigned char* scr) {
;     ...
;     for (int ks = 0; ks < 4; ++ks) {
;         bf16x8 af[2], bfr[2];
; #pragma unroll
;         for (int mt = 0; mt < 2; ++mt) { af[mt] = *(const LAS bf16x8*)(QL + (16 * mt + r) * 272 + (32 * ks + 8 * g) * 2); bfr[mt] = *(const LAS bf16x8*)(KL + (16 * mt + r) * 272 + (32 * ks + 8 * g) * 2); }
; #pragma unroll
;         for (int mt = 0; mt < 2; ++mt)
; #pragma unroll
;             for (int nt = 0; nt < 2; ++nt) acc[mt][nt] = __builtin_amdgcn_mfma_f32_16x16x32_bf16(af[mt], bfr[nt], acc[mt][nt], 0, 0, 0);
;     }
;     LDS_WAIT(); asm volatile("" ::: "memory");
; #pragma unroll
;     for (int mt = 0; mt < 2; ++mt)
; #pragma unroll
;         for (int nt = 0; nt < 2; ++nt)
; #pragma unroll
;             for (int i = 0; i < 4; ++i) { const int t = 16 * mt + 4 * g + i, s = 16 * nt + r;
;                 *(LAS bf16*)(KL + t * 80 + s * 2) = (bf16)(pk2(s <= t ? acc[mt][nt][i] : 0.f, 0.f) & 0xffffu); }
;     LDS_WAIT(); asm volatile("" ::: "memory");
; #pragma unroll
;     for (int mt = 0; mt < 2; ++mt) {
;         const LAS unsigned char* p = KL + (16 * mt + r) * 80 + (4 * g) * 2;
;         const v2u lo = *(const LAS v2u*)p, hi = *(const LAS v2u*)(p + 32);
;         *(GAS v4u*)(ha + (mt * 64 + lane) * 16) = (v4u){lo.x, lo.y, hi.x, hi.y};
; __global__ void __launch_bounds__(512, 2) mega_fwd(Args args) {
;     ...
;                 for (int r3 = 0; r3 < REPS(12); ++r3) { PH(Fp); for (int j = Fp.vcu * 8 + Fp.wave; j < 1536; j += Fp.G * 8) hgrn_prep_job(Fp, j, l, Fp.lds + Fp.wave * 17408); }
;     ...
;                 __syncthreads();
;                 for (int r3 = 0; r3 < REPS(13); ++r3) { PH(Fp); for (int j = Fp.vcu; j < 512; j += Fp.G) attn_prep_job(Fp, j); if (r3 == 0) gate_pass(Fp, l); }
	v_mfma_f32_16x16x32_bf16 v[8:11], v[12:15], v[8:11], 0
	s_waitcnt lgkmcnt(0)
	v_mfma_f32_16x16x32_bf16 v[12:15], v[12:15], v[16:19], 0
	ds_read_b128 v[16:19], v56 offset:64
	ds_read_b128 v[20:23], v56 offset:8768
	ds_read_b128 v[24:27], v56 offset:4416
	ds_read_b128 v[28:31], v56 offset:13120
	s_waitcnt lgkmcnt(2)
	v_mfma_f32_16x16x32_bf16 v[4:7], v[16:19], v[20:23], v[4:7]
	s_waitcnt lgkmcnt(1)
	v_mfma_f32_16x16x32_bf16 v[8:11], v[24:27], v[20:23], v[8:11]
	s_waitcnt lgkmcnt(0)
	v_mfma_f32_16x16x32_bf16 v[12:15], v[24:27], v[28:31], v[12:15]
	ds_read_b128 v[16:19], v56 offset:128
	ds_read_b128 v[20:23], v56 offset:8832
	ds_read_b128 v[24:27], v56 offset:4480
	ds_read_b128 v[28:31], v56 offset:13184
	s_waitcnt lgkmcnt(2)
	v_mfma_f32_16x16x32_bf16 v[4:7], v[16:19], v[20:23], v[4:7]
	s_waitcnt lgkmcnt(1)
	v_mfma_f32_16x16x32_bf16 v[8:11], v[24:27], v[20:23], v[8:11]
	s_waitcnt lgkmcnt(0)
	v_mfma_f32_16x16x32_bf16 v[12:15], v[24:27], v[28:31], v[12:15]
	ds_read_b128 v[16:19], v56 offset:192
	ds_read_b128 v[20:23], v56 offset:8896
	ds_read_b128 v[24:27], v56 offset:4544
	ds_read_b128 v[28:31], v56 offset:13248
	s_waitcnt lgkmcnt(0)
	s_waitcnt lgkmcnt(2)
	v_mfma_f32_16x16x32_bf16 v[4:7], v[16:19], v[20:23], v[4:7]
	v_add_u32_e32 v16, v52, v53
	s_waitcnt lgkmcnt(1)
	v_mfma_f32_16x16x32_bf16 v[8:11], v[24:27], v[20:23], v[8:11]
	s_waitcnt lgkmcnt(0)
	v_mfma_f32_16x16x32_bf16 v[12:15], v[24:27], v[28:31], v[12:15]
	s_nop 2
	v_cvt_pk_bf16_f32 v4, v4, s0
	v_cndmask_b32_e64 v4, v4, 0, s[40:41]
	ds_write_b16 v16, v4 offset:8704
	v_cvt_pk_bf16_f32 v4, v5, s0
	v_cndmask_b32_e64 v4, v4, 0, s[42:43]
	v_add_u32_e32 v5, v52, v54
	ds_write_b16 v5, v4 offset:8704
	v_cvt_pk_bf16_f32 v4, v6, s0
	v_cndmask_b32_e64 v4, v4, 0, s[44:45]
	ds_write_b16 v5, v4 offset:8784
	v_cvt_pk_bf16_f32 v4, v7, s0
	v_cndmask_b32_e64 v4, v4, 0, s[46:47]
	ds_write_b16 v5, v4 offset:8864
	v_add_u32_e32 v4, v55, v53
	v_add_u32_e32 v6, v55, v54
	v_cvt_pk_bf16_f32 v7, v8, s0
	ds_write_b16 v4, v97 offset:8704
	ds_write_b16 v6, v97 offset:8704
	ds_write_b16 v6, v97 offset:8784
	ds_write_b16 v6, v97 offset:8864
	ds_write_b16 v16, v7 offset:9984
	v_cvt_pk_bf16_f32 v7, v9, s0
	ds_write_b16 v5, v7 offset:9984
	v_cvt_pk_bf16_f32 v7, v10, s0
	ds_write_b16 v5, v7 offset:10064
	v_cvt_pk_bf16_f32 v7, v11, s0
	ds_write_b16 v5, v7 offset:10144
	v_cvt_pk_bf16_f32 v5, v12, s0
	v_cndmask_b32_e64 v5, v5, 0, s[40:41]
	ds_write_b16 v4, v5 offset:9984
	v_cvt_pk_bf16_f32 v4, v13, s0
	v_cndmask_b32_e64 v4, v4, 0, s[48:49]
	ds_write_b16 v6, v4 offset:9984
	v_cvt_pk_bf16_f32 v4, v14, s0
	v_cndmask_b32_e64 v4, v4, 0, s[50:51]
	ds_write_b16 v6, v4 offset:10064
	v_cvt_pk_bf16_f32 v4, v15, s0
	v_cndmask_b32_e64 v4, v4, 0, s[52:53]
	ds_write_b16 v6, v4 offset:10144
	s_waitcnt lgkmcnt(0)
	v_add_u32_e32 v10, 0x2000, v57
	ds_read2_b64 v[4:7], v10 offset0:64 offset1:68
	s_lshl_b64 s[0:1], s[54:55], 11
	v_lshl_add_u64 v[8:9], v[2:3], 0, s[0:1]
	v_readlane_b32 s0, v253, 34
	s_add_i32 s30, s30, s0
	s_waitcnt lgkmcnt(0)
	global_store_dwordx4 v[8:9], v[4:7], off
	ds_read2_b64 v[4:7], v10 offset0:224 offset1:228
	s_cmpk_gt_i32 s30, 0x5ff
	v_readlane_b32 s1, v253, 35
	s_waitcnt lgkmcnt(0)
	global_store_dwordx4 v[8:9], v[4:7], off offset:1024
	s_waitcnt lgkmcnt(0)
	s_cbranch_scc0 .LBB0_809
.LBB0_812:
	s_barrier
	v_mbcnt_lo_u32_b32 v0, -1, 0
	v_mbcnt_hi_u32_b32 v0, -1, v0
	s_mov_b64 s[0:1], s[86:87]
	v_add_u32_e32 v9, s81, v0
	s_mov_b64 s[30:31], s[84:85]
	v_readlane_b32 s82, v252, 7
	v_readlane_b32 s34, v253, 36
	v_readlane_b32 s83, v252, 8
	v_readlane_b32 s35, v253, 37
	s_mov_b64 s[30:31], s[82:83]
	s_and_b64 vcc, exec, s[34:35]
	v_readlane_b32 s95, v255, 16
	v_readlane_b32 s50, v253, 40
	v_readlane_b32 s51, v254, 1
	s_mov_b32 s52, 0x2aaaaaab
	s_mov_b32 s80, 0x4b800000
	s_mov_b32 s53, 0x60000
	s_movk_i32 s78, 0x1fff
	s_mov_b32 s54, 0x3e38aa3b
	s_mov_b64 s[56:57], 0x32503600
	s_cbranch_vccz .LBB0_815
	v_ashrrev_i32_e32 v11, 3, v9
	v_lshlrev_b32_e32 v1, 5, v9
	v_and_b32_e32 v6, 0xfffff00, v9
	v_and_b32_e32 v0, 31, v11
	v_and_b32_e32 v5, 64, v1
	v_and_or_b32 v1, v1, 32, v6
	v_and_b32_e32 v2, 3, v9
	v_or3_b32 v0, v1, v0, v5
	v_bfe_u32 v3, v9, 2, 1
	v_lshlrev_b32_e32 v0, 4, v0
	v_lshlrev_b32_e32 v96, 4, v2
	v_lshlrev_b32_e32 v8, 3, v2
	v_lshlrev_b32_e32 v10, 6, v3
	v_ashrrev_i32_e32 v1, 31, v0
	v_lshlrev_b32_e32 v12, 12, v3
	v_lshl_add_u64 v[2:3], s[0:1], 0, v[96:97]
	s_mov_b64 s[38:39], 0x3be90000
	v_lshl_add_u64 v[14:15], v[2:3], 0, s[38:39]
	v_lshl_add_u64 v[0:1], s[0:1], 0, v[0:1]
	s_mov_b64 s[38:39], 0x3c690000
	v_lshrrev_b32_e32 v2, 5, v9
	v_lshl_add_u64 v[16:17], v[0:1], 0, s[38:39]
	v_lshrrev_b32_e32 v1, 4, v9
	v_and_b32_e32 v2, 4, v2
	v_and_or_b32 v13, v1, 16, v2
	v_ashrrev_i32_e32 v2, 4, v9
	v_and_b32_e32 v18, 0xffffffe0, v2
	v_add_u32_e32 v2, 0x200, v9
	v_ashrrev_i32_e32 v2, 4, v2
	s_add_u32 s34, s0, 0x3bd80000
	v_lshrrev_b32_e32 v4, 2, v9
	v_and_b32_e32 v20, 0xffffffe0, v2
	v_and_b32_e32 v2, 31, v9
	s_movk_i32 s2, 0x60
	s_addc_u32 s35, s1, 0
	v_and_b32_e32 v1, 6, v1
	v_and_or_b32 v2, v4, s2, v2
	v_lshrrev_b32_e32 v3, 9, v9
	s_add_u32 s40, s0, 0x32500000
	v_add_u32_e32 v1, v1, v3
	v_lshlrev_b32_e32 v2, 4, v2
	s_addc_u32 s41, s1, 0
	v_lshl_or_b32 v22, v1, 11, v2
	s_add_u32 s36, s0, 0x3ce90000
	v_and_b32_e32 v0, 0x7f, v9
	v_add_u32_e32 v24, 0x800, v22
	s_addc_u32 s38, s1, 0
	v_ashrrev_i32_e32 v19, 31, v18
	v_ashrrev_i32_e32 v21, 31, v20
	v_ashrrev_i32_e32 v23, 31, v22
	v_ashrrev_i32_e32 v25, 31, v24
	v_lshlrev_b32_e32 v26, 1, v0
	v_readlane_b32 s39, v252, 2
	s_movk_i32 s98, 64
	s_movk_i32 s99, 0x140
	s_sub_i32 s39, s39, 0xc0
	s_cmp_ge_i32 s39, 0
	s_cbranch_scc1 .Lap_go
	s_add_i32 s39, s39, 0x200
	s_movk_i32 s98, 0x400
	s_movk_i32 s99, 0x200
	s_cmp_lt_i32 s39, s99
	s_cbranch_scc0 .LBB0_815
